# epilogue stores of P1/P3/P4/P5 transposed through per-wave LDS scratch so 4 adjacent lanes write one 64B row segment
# speedup vs baseline: 1.0053x; 1.0053x over previous
.LBB0_234:
	s_or_b64 exec, exec, s[4:5]
	v_mov_b32_e32 v8, v172
	v_and_b32_e32 v244, 63, v172
	v_lshrrev_b32_e32 v245, 6, v172
	v_mul_u32_u24_e32 v245, 0x7e0, v245
	v_add_u32_e32 v245, 0x20000, v245
	v_and_b32_e32 v246, 15, v244
	v_lshrrev_b32_e32 v230, 4, v244
	v_bfe_u32 v231, v246, 1, 2
	v_xor_b32_e32 v230, v230, v231
	v_lshlrev_b32_e32 v230, 4, v230
	v_lshl_add_u32 v230, v246, 6, v230
	v_add_u32_e32 v230, v230, v245
	v_lshrrev_b32_e32 v246, 2, v244
	v_and_b32_e32 v231, 3, v244
	v_bfe_u32 v232, v246, 1, 2
	v_xor_b32_e32 v231, v231, v232
	v_lshlrev_b32_e32 v231, 4, v231
	v_lshl_add_u32 v231, v246, 6, v231
	v_add_u32_e32 v231, v231, v245
	v_and_b32_e32 v232, 3, v244
	v_lshlrev_b32_e32 v232, 4, v232
	v_mul_u32_u24_e32 v246, 0xe00, v246
	v_add_u32_e32 v232, v232, v246
	v_and_b32_e32 v233, 3, v244
	v_lshlrev_b32_e32 v233, 4, v233
	v_lshrrev_b32_e32 v246, 2, v244
	v_lshl_add_u32 v233, v246, 11, v233
	s_cmpk_lt_i32 s33, 0x380
	s_waitcnt lgkmcnt(0)
	s_barrier
	s_cselect_b64 s[4:5], -1, 0
	s_cmpk_gt_i32 s33, 0x37f
	v_readfirstlane_b32 s18, v8
	s_cbranch_scc1 .LBB0_236
	s_ashr_i32 s2, s33, 31
	s_lshr_b32 s2, s2, 29
	s_add_i32 s2, s33, s2
	s_ashr_i32 s6, s2, 3
	s_and_b32 s2, s2, -8
	s_sub_i32 s2, s33, s2
	s_cmp_lt_i32 s2, 0
	s_movk_i32 s7, 0x71
	s_cselect_b32 s7, s7, 0x70
	s_mul_i32 s2, s2, s7
	s_add_i32 s2, s2, s6
	s_mul_hi_i32 s6, s2, 0x92492493
	s_add_i32 s6, s6, s2
	s_lshr_b32 s7, s6, 31
	s_ashr_i32 s6, s6, 4
	s_add_i32 s6, s6, s7
	s_lshl_b32 s7, s6, 2
	s_mul_i32 s6, s6, 28
	s_sub_i32 s2, s2, s6
	s_bfe_i32 s6, s2, 0x80000
	s_bfe_u32 s6, s6, 0x2000d
	s_add_i32 s6, s2, s6
	s_bfe_i32 s8, s6, 0x80000
	s_and_b32 s6, s6, 0xfc
	s_sub_i32 s2, s2, s6
	s_sext_i32_i16 s8, s8
	s_sext_i32_i8 s2, s2
	s_add_i32 s42, s7, s2
	s_ashr_i32 s6, s8, 2

.LBB0_250:
	v_lshl_or_b32 v120, s6, 8, v177
	v_mov_b64_e32 v[122:123], s[12:13]
	v_cvt_pk_bf16_f32 v168, v168, v169
	v_cvt_pk_bf16_f32 v169, v126, v127
	v_cvt_pk_bf16_f32 v170, v170, v171
	v_cvt_pk_bf16_f32 v171, v124, v125
	v_mov_b32_e32 v124, v166
	v_mov_b32_e32 v125, v166
	v_mov_b32_e32 v167, v166
	v_ashrrev_i32_e32 v121, 31, v120
	v_mad_i64_i32 v[122:123], s[6:7], v146, s60, v[122:123]
	v_pk_mul_f32 v[118:119], v[118:119], v[124:125]
	v_pk_mul_f32 v[114:115], v[114:115], v[124:125]
	v_cndmask_b32_e64 v124, 0, 1, s[42:43]
	v_lshl_add_u64 v[122:123], v[120:121], 1, v[122:123]
	v_pk_mul_f32 v[116:117], v[116:117], v[166:167]
	v_cmp_ne_u32_e64 s[6:7], 1, v124
	s_andn2_b64 vcc, exec, s[42:43]
	v_pk_mul_f32 v[112:113], v[112:113], v[166:167]
	s_nop 0
	v_readfirstlane_b32 s82, v122
	v_readfirstlane_b32 s83, v123
	ds_write_b128 v230, v[168:171]
	ds_read_b128 v[236:239], v231
	s_nop 1
	s_waitcnt lgkmcnt(0)
	global_store_dwordx4 v232, v[236:239], s[82:83]
	s_cbranch_vccnz .LBB0_252
	v_pk_mul_f32 v[124:125], v[118:119], v[118:119]
	v_pk_mul_f32 v[126:127], v[116:117], v[116:117]
	v_mov_b64_e32 v[166:167], s[22:23]
	v_pk_mul_f32 v[168:169], v[114:115], v[114:115]
	v_pk_mul_f32 v[170:171], v[112:113], v[112:113]
	v_pk_fma_f32 v[126:127], v[126:127], s[20:21], v[166:167] op_sel_hi:[1,0,0] neg_lo:[1,0,0] neg_hi:[1,0,0]
	v_pk_fma_f32 v[124:125], v[124:125], s[20:21], v[166:167] op_sel_hi:[1,0,0] neg_lo:[1,0,0] neg_hi:[1,0,0]
	v_pk_fma_f32 v[170:171], v[170:171], s[20:21], v[166:167] op_sel_hi:[1,0,0] neg_lo:[1,0,0] neg_hi:[1,0,0]
	v_pk_fma_f32 v[166:167], v[168:169], s[20:21], v[166:167] op_sel_hi:[1,0,0] neg_lo:[1,0,0] neg_hi:[1,0,0]
	v_pk_mul_f32 v[126:127], v[116:117], v[126:127]
	v_pk_mul_f32 v[124:125], v[118:119], v[124:125]
	v_pk_mul_f32 v[170:171], v[112:113], v[170:171]
	v_pk_mul_f32 v[166:167], v[114:115], v[166:167]
	v_exp_f32_e32 v126, v126
	v_exp_f32_e32 v127, v127
	v_exp_f32_e32 v124, v124
	v_exp_f32_e32 v125, v125
	v_exp_f32_e32 v170, v170
	v_exp_f32_e32 v171, v171
	v_exp_f32_e32 v166, v166
	v_exp_f32_e32 v167, v167
	v_pk_add_f32 v[126:127], v[126:127], 1.0 op_sel_hi:[1,0]
	v_pk_add_f32 v[124:125], v[124:125], 1.0 op_sel_hi:[1,0]
	v_pk_add_f32 v[168:169], v[170:171], 1.0 op_sel_hi:[1,0]
	v_pk_add_f32 v[166:167], v[166:167], 1.0 op_sel_hi:[1,0]
	v_rcp_f32_e32 v126, v126
	v_rcp_f32_e32 v127, v127
	v_rcp_f32_e32 v124, v124
	v_rcp_f32_e32 v125, v125
	v_rcp_f32_e32 v168, v168
	v_rcp_f32_e32 v166, v166
	v_rcp_f32_e32 v167, v167
	v_rcp_f32_e32 v169, v169
	v_pk_mul_f32 v[118:119], v[118:119], v[124:125]
	v_pk_mul_f32 v[116:117], v[116:117], v[126:127]
	v_pk_mul_f32 v[114:115], v[114:115], v[166:167]
	v_pk_mul_f32 v[112:113], v[112:113], v[168:169]
.LBB0_252:
	v_cvt_pk_bf16_f32 v116, v116, v117
	v_cvt_pk_bf16_f32 v117, v118, v119
	s_nop 0
	v_cvt_pk_bf16_f32 v118, v112, v113
	v_pk_mul_f32 v[110:111], v[110:111], v[162:163] op_sel_hi:[1,0]
	v_pk_mul_f32 v[108:109], v[108:109], v[162:163] op_sel_hi:[1,0]
	v_pk_mul_f32 v[106:107], v[106:107], v[162:163] op_sel_hi:[1,0]
	s_and_b64 vcc, exec, s[6:7]
	v_pk_mul_f32 v[112:113], v[104:105], v[162:163] op_sel_hi:[1,0]
	v_cvt_pk_bf16_f32 v119, v114, v115
	s_nop 0
	v_readfirstlane_b32 s84, v122
	v_readfirstlane_b32 s85, v123
	ds_write_b128 v230, v[116:119]
	ds_read_b128 v[240:243], v231
	s_nop 1
	s_waitcnt lgkmcnt(0)
	global_store_dwordx4 v232, v[240:243], s[84:85] offset:256
	s_cbranch_vccnz .LBB0_254
	v_pk_mul_f32 v[104:105], v[110:111], v[110:111]
	v_pk_mul_f32 v[114:115], v[108:109], v[108:109]
	v_mov_b64_e32 v[116:117], s[22:23]
	v_pk_mul_f32 v[118:119], v[106:107], v[106:107]
	v_pk_mul_f32 v[122:123], v[112:113], v[112:113]
	v_pk_fma_f32 v[114:115], v[114:115], s[20:21], v[116:117] op_sel_hi:[1,0,0] neg_lo:[1,0,0] neg_hi:[1,0,0]
	v_pk_fma_f32 v[104:105], v[104:105], s[20:21], v[116:117] op_sel_hi:[1,0,0] neg_lo:[1,0,0] neg_hi:[1,0,0]
	v_pk_fma_f32 v[122:123], v[122:123], s[20:21], v[116:117] op_sel_hi:[1,0,0] neg_lo:[1,0,0] neg_hi:[1,0,0]
	v_pk_fma_f32 v[116:117], v[118:119], s[20:21], v[116:117] op_sel_hi:[1,0,0] neg_lo:[1,0,0] neg_hi:[1,0,0]
	v_pk_mul_f32 v[114:115], v[108:109], v[114:115]
	v_pk_mul_f32 v[104:105], v[110:111], v[104:105]
	v_pk_mul_f32 v[122:123], v[112:113], v[122:123]
	v_pk_mul_f32 v[116:117], v[106:107], v[116:117]
	v_exp_f32_e32 v114, v114
	v_exp_f32_e32 v115, v115
	v_exp_f32_e32 v104, v104
	v_exp_f32_e32 v105, v105
	v_exp_f32_e32 v122, v122
	v_exp_f32_e32 v123, v123
	v_exp_f32_e32 v116, v116
	v_exp_f32_e32 v117, v117
	v_pk_add_f32 v[114:115], v[114:115], 1.0 op_sel_hi:[1,0]
	v_pk_add_f32 v[104:105], v[104:105], 1.0 op_sel_hi:[1,0]
	v_pk_add_f32 v[118:119], v[122:123], 1.0 op_sel_hi:[1,0]
	v_pk_add_f32 v[116:117], v[116:117], 1.0 op_sel_hi:[1,0]
	v_rcp_f32_e32 v114, v114
	v_rcp_f32_e32 v115, v115
	v_rcp_f32_e32 v104, v104
	v_rcp_f32_e32 v105, v105
	v_rcp_f32_e32 v118, v118
	v_rcp_f32_e32 v116, v116
	v_rcp_f32_e32 v117, v117
	v_rcp_f32_e32 v119, v119
	v_pk_mul_f32 v[110:111], v[110:111], v[104:105]
	v_pk_mul_f32 v[108:109], v[108:109], v[114:115]
	v_pk_mul_f32 v[106:107], v[106:107], v[116:117]
	v_pk_mul_f32 v[112:113], v[112:113], v[118:119]
.LBB0_254:
	v_mov_b64_e32 v[104:105], s[12:13]
	v_mov_b32_e32 v163, v162
	v_mad_i64_i32 v[104:105], s[42:43], v164, s60, v[104:105]
	v_cvt_pk_bf16_f32 v108, v108, v109
	v_cvt_pk_bf16_f32 v109, v110, v111
	v_cvt_pk_bf16_f32 v110, v112, v113
	v_cvt_pk_bf16_f32 v111, v106, v107
	v_mov_b32_e32 v106, v162
	v_mov_b32_e32 v107, v162
	v_lshl_add_u64 v[104:105], v[120:121], 1, v[104:105]
	v_pk_mul_f32 v[102:103], v[102:103], v[106:107]
	v_pk_mul_f32 v[100:101], v[100:101], v[162:163]
	v_pk_mul_f32 v[98:99], v[98:99], v[106:107]
	s_and_b64 vcc, exec, s[6:7]
	v_pk_mul_f32 v[96:97], v[96:97], v[162:163]
	s_nop 0
	v_readfirstlane_b32 s82, v104
	v_readfirstlane_b32 s83, v105
	ds_write_b128 v230, v[108:111]
	ds_read_b128 v[236:239], v231
	s_nop 1
	s_waitcnt lgkmcnt(0)
	global_store_dwordx4 v232, v[236:239], s[82:83]
	s_cbranch_vccnz .LBB0_256
	v_pk_mul_f32 v[106:107], v[102:103], v[102:103]
	v_pk_mul_f32 v[108:109], v[100:101], v[100:101]
	v_mov_b64_e32 v[110:111], s[22:23]
	v_pk_mul_f32 v[112:113], v[98:99], v[98:99]
	v_pk_mul_f32 v[114:115], v[96:97], v[96:97]
	v_pk_fma_f32 v[108:109], v[108:109], s[20:21], v[110:111] op_sel_hi:[1,0,0] neg_lo:[1,0,0] neg_hi:[1,0,0]
	v_pk_fma_f32 v[106:107], v[106:107], s[20:21], v[110:111] op_sel_hi:[1,0,0] neg_lo:[1,0,0] neg_hi:[1,0,0]
	v_pk_fma_f32 v[114:115], v[114:115], s[20:21], v[110:111] op_sel_hi:[1,0,0] neg_lo:[1,0,0] neg_hi:[1,0,0]
	v_pk_fma_f32 v[110:111], v[112:113], s[20:21], v[110:111] op_sel_hi:[1,0,0] neg_lo:[1,0,0] neg_hi:[1,0,0]
	v_pk_mul_f32 v[108:109], v[100:101], v[108:109]
	v_pk_mul_f32 v[106:107], v[102:103], v[106:107]
	v_pk_mul_f32 v[114:115], v[96:97], v[114:115]
	v_pk_mul_f32 v[110:111], v[98:99], v[110:111]
	v_exp_f32_e32 v108, v108
	v_exp_f32_e32 v109, v109
	v_exp_f32_e32 v106, v106
	v_exp_f32_e32 v107, v107
	v_exp_f32_e32 v114, v114
	v_exp_f32_e32 v115, v115
	v_exp_f32_e32 v110, v110
	v_exp_f32_e32 v111, v111
	v_pk_add_f32 v[108:109], v[108:109], 1.0 op_sel_hi:[1,0]
	v_pk_add_f32 v[106:107], v[106:107], 1.0 op_sel_hi:[1,0]
	v_pk_add_f32 v[112:113], v[114:115], 1.0 op_sel_hi:[1,0]
	v_pk_add_f32 v[110:111], v[110:111], 1.0 op_sel_hi:[1,0]
	v_rcp_f32_e32 v108, v108
	v_rcp_f32_e32 v109, v109
	v_rcp_f32_e32 v106, v106
	v_rcp_f32_e32 v107, v107
	v_rcp_f32_e32 v112, v112
	v_rcp_f32_e32 v110, v110
	v_rcp_f32_e32 v111, v111
	v_rcp_f32_e32 v113, v113
	v_pk_mul_f32 v[102:103], v[102:103], v[106:107]
	v_pk_mul_f32 v[100:101], v[100:101], v[108:109]
	v_pk_mul_f32 v[98:99], v[98:99], v[110:111]
	v_pk_mul_f32 v[96:97], v[96:97], v[112:113]
.LBB0_256:
	v_cvt_pk_bf16_f32 v100, v100, v101
	v_cvt_pk_bf16_f32 v101, v102, v103
	s_nop 0
	v_cvt_pk_bf16_f32 v102, v96, v97
	v_pk_mul_f32 v[94:95], v[94:95], v[158:159] op_sel_hi:[1,0]
	v_pk_mul_f32 v[92:93], v[92:93], v[158:159] op_sel_hi:[1,0]
	v_pk_mul_f32 v[90:91], v[90:91], v[158:159] op_sel_hi:[1,0]
	s_and_b64 vcc, exec, s[6:7]
	v_pk_mul_f32 v[96:97], v[88:89], v[158:159] op_sel_hi:[1,0]
	v_cvt_pk_bf16_f32 v103, v98, v99
	s_nop 0
	v_readfirstlane_b32 s84, v104
	v_readfirstlane_b32 s85, v105
	ds_write_b128 v230, v[100:103]
	ds_read_b128 v[240:243], v231
	s_nop 1
	s_waitcnt lgkmcnt(0)
	global_store_dwordx4 v232, v[240:243], s[84:85] offset:256
	s_cbranch_vccnz .LBB0_258
	v_pk_mul_f32 v[88:89], v[94:95], v[94:95]
	v_pk_mul_f32 v[98:99], v[92:93], v[92:93]
	v_mov_b64_e32 v[100:101], s[22:23]
	v_pk_mul_f32 v[102:103], v[90:91], v[90:91]
	v_pk_mul_f32 v[104:105], v[96:97], v[96:97]
	v_pk_fma_f32 v[98:99], v[98:99], s[20:21], v[100:101] op_sel_hi:[1,0,0] neg_lo:[1,0,0] neg_hi:[1,0,0]
	v_pk_fma_f32 v[88:89], v[88:89], s[20:21], v[100:101] op_sel_hi:[1,0,0] neg_lo:[1,0,0] neg_hi:[1,0,0]
	v_pk_fma_f32 v[104:105], v[104:105], s[20:21], v[100:101] op_sel_hi:[1,0,0] neg_lo:[1,0,0] neg_hi:[1,0,0]
	v_pk_fma_f32 v[100:101], v[102:103], s[20:21], v[100:101] op_sel_hi:[1,0,0] neg_lo:[1,0,0] neg_hi:[1,0,0]
	v_pk_mul_f32 v[98:99], v[92:93], v[98:99]
	v_pk_mul_f32 v[88:89], v[94:95], v[88:89]
	v_pk_mul_f32 v[104:105], v[96:97], v[104:105]
	v_pk_mul_f32 v[100:101], v[90:91], v[100:101]
	v_exp_f32_e32 v98, v98
	v_exp_f32_e32 v99, v99
	v_exp_f32_e32 v88, v88
	v_exp_f32_e32 v89, v89
	v_exp_f32_e32 v104, v104
	v_exp_f32_e32 v105, v105
	v_exp_f32_e32 v100, v100
	v_exp_f32_e32 v101, v101
	v_pk_add_f32 v[98:99], v[98:99], 1.0 op_sel_hi:[1,0]
	v_pk_add_f32 v[88:89], v[88:89], 1.0 op_sel_hi:[1,0]
	v_pk_add_f32 v[102:103], v[104:105], 1.0 op_sel_hi:[1,0]
	v_pk_add_f32 v[100:101], v[100:101], 1.0 op_sel_hi:[1,0]
	v_rcp_f32_e32 v98, v98
	v_rcp_f32_e32 v99, v99
	v_rcp_f32_e32 v88, v88
	v_rcp_f32_e32 v89, v89
	v_rcp_f32_e32 v102, v102
	v_rcp_f32_e32 v100, v100
	v_rcp_f32_e32 v101, v101
	v_rcp_f32_e32 v103, v103
	v_pk_mul_f32 v[94:95], v[94:95], v[88:89]
	v_pk_mul_f32 v[92:93], v[92:93], v[98:99]
	v_pk_mul_f32 v[90:91], v[90:91], v[100:101]
	v_pk_mul_f32 v[96:97], v[96:97], v[102:103]
.LBB0_258:
	v_mov_b64_e32 v[88:89], s[12:13]
	v_mov_b32_e32 v159, v158
	v_mad_i64_i32 v[88:89], s[42:43], v160, s60, v[88:89]
	v_cvt_pk_bf16_f32 v92, v92, v93
	v_cvt_pk_bf16_f32 v93, v94, v95
	v_cvt_pk_bf16_f32 v94, v96, v97
	v_cvt_pk_bf16_f32 v95, v90, v91
	v_mov_b32_e32 v90, v158
	v_mov_b32_e32 v91, v158
	v_lshl_add_u64 v[88:89], v[120:121], 1, v[88:89]
	v_pk_mul_f32 v[86:87], v[86:87], v[90:91]
	v_pk_mul_f32 v[84:85], v[84:85], v[158:159]
	v_pk_mul_f32 v[82:83], v[82:83], v[90:91]
	s_and_b64 vcc, exec, s[6:7]
	v_pk_mul_f32 v[80:81], v[80:81], v[158:159]
	s_nop 0
	v_readfirstlane_b32 s82, v88
	v_readfirstlane_b32 s83, v89
	ds_write_b128 v230, v[92:95]
	ds_read_b128 v[236:239], v231
	s_nop 1
	s_waitcnt lgkmcnt(0)
	global_store_dwordx4 v232, v[236:239], s[82:83]
	s_cbranch_vccnz .LBB0_260
	v_pk_mul_f32 v[90:91], v[86:87], v[86:87]
	v_pk_mul_f32 v[92:93], v[84:85], v[84:85]
	v_mov_b64_e32 v[94:95], s[22:23]
	v_pk_mul_f32 v[96:97], v[82:83], v[82:83]
	v_pk_mul_f32 v[98:99], v[80:81], v[80:81]
	v_pk_fma_f32 v[92:93], v[92:93], s[20:21], v[94:95] op_sel_hi:[1,0,0] neg_lo:[1,0,0] neg_hi:[1,0,0]
	v_pk_fma_f32 v[90:91], v[90:91], s[20:21], v[94:95] op_sel_hi:[1,0,0] neg_lo:[1,0,0] neg_hi:[1,0,0]
	v_pk_fma_f32 v[98:99], v[98:99], s[20:21], v[94:95] op_sel_hi:[1,0,0] neg_lo:[1,0,0] neg_hi:[1,0,0]
	v_pk_fma_f32 v[94:95], v[96:97], s[20:21], v[94:95] op_sel_hi:[1,0,0] neg_lo:[1,0,0] neg_hi:[1,0,0]
	v_pk_mul_f32 v[92:93], v[84:85], v[92:93]
	v_pk_mul_f32 v[90:91], v[86:87], v[90:91]
	v_pk_mul_f32 v[98:99], v[80:81], v[98:99]
	v_pk_mul_f32 v[94:95], v[82:83], v[94:95]
	v_exp_f32_e32 v92, v92
	v_exp_f32_e32 v93, v93
	v_exp_f32_e32 v90, v90
	v_exp_f32_e32 v91, v91
	v_exp_f32_e32 v98, v98
	v_exp_f32_e32 v99, v99
	v_exp_f32_e32 v94, v94
	v_exp_f32_e32 v95, v95
	v_pk_add_f32 v[92:93], v[92:93], 1.0 op_sel_hi:[1,0]
	v_pk_add_f32 v[90:91], v[90:91], 1.0 op_sel_hi:[1,0]
	v_pk_add_f32 v[96:97], v[98:99], 1.0 op_sel_hi:[1,0]
	v_pk_add_f32 v[94:95], v[94:95], 1.0 op_sel_hi:[1,0]
	v_rcp_f32_e32 v92, v92
	v_rcp_f32_e32 v93, v93
	v_rcp_f32_e32 v90, v90
	v_rcp_f32_e32 v91, v91
	v_rcp_f32_e32 v96, v96
	v_rcp_f32_e32 v94, v94
	v_rcp_f32_e32 v95, v95
	v_rcp_f32_e32 v97, v97
	v_pk_mul_f32 v[86:87], v[86:87], v[90:91]
	v_pk_mul_f32 v[84:85], v[84:85], v[92:93]
	v_pk_mul_f32 v[82:83], v[82:83], v[94:95]
	v_pk_mul_f32 v[80:81], v[80:81], v[96:97]
.LBB0_260:
	v_cvt_pk_bf16_f32 v84, v84, v85
	v_cvt_pk_bf16_f32 v85, v86, v87
	s_nop 0
	v_cvt_pk_bf16_f32 v86, v80, v81
	v_pk_mul_f32 v[78:79], v[78:79], v[154:155] op_sel_hi:[1,0]
	v_pk_mul_f32 v[76:77], v[76:77], v[154:155] op_sel_hi:[1,0]
	v_pk_mul_f32 v[74:75], v[74:75], v[154:155] op_sel_hi:[1,0]
	s_and_b64 vcc, exec, s[6:7]
	v_pk_mul_f32 v[80:81], v[72:73], v[154:155] op_sel_hi:[1,0]
	v_cvt_pk_bf16_f32 v87, v82, v83
	s_nop 0
	v_readfirstlane_b32 s84, v88
	v_readfirstlane_b32 s85, v89
	ds_write_b128 v230, v[84:87]
	ds_read_b128 v[240:243], v231
	s_nop 1
	s_waitcnt lgkmcnt(0)
	global_store_dwordx4 v232, v[240:243], s[84:85] offset:256
	s_cbranch_vccnz .LBB0_262
	v_pk_mul_f32 v[72:73], v[78:79], v[78:79]
	v_pk_mul_f32 v[82:83], v[76:77], v[76:77]
	v_mov_b64_e32 v[84:85], s[22:23]
	v_pk_mul_f32 v[86:87], v[74:75], v[74:75]
	v_pk_mul_f32 v[88:89], v[80:81], v[80:81]
	v_pk_fma_f32 v[82:83], v[82:83], s[20:21], v[84:85] op_sel_hi:[1,0,0] neg_lo:[1,0,0] neg_hi:[1,0,0]
	v_pk_fma_f32 v[72:73], v[72:73], s[20:21], v[84:85] op_sel_hi:[1,0,0] neg_lo:[1,0,0] neg_hi:[1,0,0]
	v_pk_fma_f32 v[88:89], v[88:89], s[20:21], v[84:85] op_sel_hi:[1,0,0] neg_lo:[1,0,0] neg_hi:[1,0,0]
	v_pk_fma_f32 v[84:85], v[86:87], s[20:21], v[84:85] op_sel_hi:[1,0,0] neg_lo:[1,0,0] neg_hi:[1,0,0]
	v_pk_mul_f32 v[82:83], v[76:77], v[82:83]
	v_pk_mul_f32 v[72:73], v[78:79], v[72:73]
	v_pk_mul_f32 v[88:89], v[80:81], v[88:89]
	v_pk_mul_f32 v[84:85], v[74:75], v[84:85]
	v_exp_f32_e32 v82, v82
	v_exp_f32_e32 v83, v83
	v_exp_f32_e32 v72, v72
	v_exp_f32_e32 v73, v73
	v_exp_f32_e32 v88, v88
	v_exp_f32_e32 v89, v89
	v_exp_f32_e32 v84, v84
	v_exp_f32_e32 v85, v85
	v_pk_add_f32 v[82:83], v[82:83], 1.0 op_sel_hi:[1,0]
	v_pk_add_f32 v[72:73], v[72:73], 1.0 op_sel_hi:[1,0]
	v_pk_add_f32 v[86:87], v[88:89], 1.0 op_sel_hi:[1,0]
	v_pk_add_f32 v[84:85], v[84:85], 1.0 op_sel_hi:[1,0]
	v_rcp_f32_e32 v82, v82
	v_rcp_f32_e32 v83, v83
	v_rcp_f32_e32 v72, v72
	v_rcp_f32_e32 v73, v73
	v_rcp_f32_e32 v86, v86
	v_rcp_f32_e32 v84, v84
	v_rcp_f32_e32 v85, v85
	v_rcp_f32_e32 v87, v87
	v_pk_mul_f32 v[78:79], v[78:79], v[72:73]
	v_pk_mul_f32 v[76:77], v[76:77], v[82:83]
	v_pk_mul_f32 v[74:75], v[74:75], v[84:85]
	v_pk_mul_f32 v[80:81], v[80:81], v[86:87]
.LBB0_262:
	v_mov_b64_e32 v[72:73], s[12:13]
	v_mov_b32_e32 v155, v154
	v_mad_i64_i32 v[72:73], s[42:43], v156, s60, v[72:73]
	v_cvt_pk_bf16_f32 v76, v76, v77
	v_cvt_pk_bf16_f32 v77, v78, v79
	v_cvt_pk_bf16_f32 v78, v80, v81
	v_cvt_pk_bf16_f32 v79, v74, v75
	v_mov_b32_e32 v74, v154
	v_mov_b32_e32 v75, v154
	v_lshl_add_u64 v[72:73], v[120:121], 1, v[72:73]
	v_pk_mul_f32 v[70:71], v[70:71], v[74:75]
	v_pk_mul_f32 v[68:69], v[68:69], v[154:155]
	v_pk_mul_f32 v[66:67], v[66:67], v[74:75]
	s_and_b64 vcc, exec, s[6:7]
	v_pk_mul_f32 v[64:65], v[64:65], v[154:155]
	s_nop 0
	v_readfirstlane_b32 s82, v72
	v_readfirstlane_b32 s83, v73
	ds_write_b128 v230, v[76:79]
	ds_read_b128 v[236:239], v231
	s_nop 1
	s_waitcnt lgkmcnt(0)
	global_store_dwordx4 v232, v[236:239], s[82:83]
	s_cbranch_vccnz .LBB0_264
	v_pk_mul_f32 v[74:75], v[70:71], v[70:71]
	v_pk_mul_f32 v[76:77], v[68:69], v[68:69]
	v_mov_b64_e32 v[78:79], s[22:23]
	v_pk_mul_f32 v[80:81], v[66:67], v[66:67]
	v_pk_mul_f32 v[82:83], v[64:65], v[64:65]
	v_pk_fma_f32 v[76:77], v[76:77], s[20:21], v[78:79] op_sel_hi:[1,0,0] neg_lo:[1,0,0] neg_hi:[1,0,0]
	v_pk_fma_f32 v[74:75], v[74:75], s[20:21], v[78:79] op_sel_hi:[1,0,0] neg_lo:[1,0,0] neg_hi:[1,0,0]
	v_pk_fma_f32 v[82:83], v[82:83], s[20:21], v[78:79] op_sel_hi:[1,0,0] neg_lo:[1,0,0] neg_hi:[1,0,0]
	v_pk_fma_f32 v[78:79], v[80:81], s[20:21], v[78:79] op_sel_hi:[1,0,0] neg_lo:[1,0,0] neg_hi:[1,0,0]
	v_pk_mul_f32 v[76:77], v[68:69], v[76:77]
	v_pk_mul_f32 v[74:75], v[70:71], v[74:75]
	v_pk_mul_f32 v[82:83], v[64:65], v[82:83]
	v_pk_mul_f32 v[78:79], v[66:67], v[78:79]
	v_exp_f32_e32 v76, v76
	v_exp_f32_e32 v77, v77
	v_exp_f32_e32 v74, v74
	v_exp_f32_e32 v75, v75
	v_exp_f32_e32 v82, v82
	v_exp_f32_e32 v83, v83
	v_exp_f32_e32 v78, v78
	v_exp_f32_e32 v79, v79
	v_pk_add_f32 v[76:77], v[76:77], 1.0 op_sel_hi:[1,0]
	v_pk_add_f32 v[74:75], v[74:75], 1.0 op_sel_hi:[1,0]
	v_pk_add_f32 v[80:81], v[82:83], 1.0 op_sel_hi:[1,0]
	v_pk_add_f32 v[78:79], v[78:79], 1.0 op_sel_hi:[1,0]
	v_rcp_f32_e32 v76, v76
	v_rcp_f32_e32 v77, v77
	v_rcp_f32_e32 v74, v74
	v_rcp_f32_e32 v75, v75
	v_rcp_f32_e32 v80, v80
	v_rcp_f32_e32 v78, v78
	v_rcp_f32_e32 v79, v79
	v_rcp_f32_e32 v81, v81
	v_pk_mul_f32 v[70:71], v[70:71], v[74:75]
	v_pk_mul_f32 v[68:69], v[68:69], v[76:77]
	v_pk_mul_f32 v[66:67], v[66:67], v[78:79]
	v_pk_mul_f32 v[64:65], v[64:65], v[80:81]
.LBB0_264:
	v_cvt_pk_bf16_f32 v68, v68, v69
	v_cvt_pk_bf16_f32 v69, v70, v71
	s_nop 0
	v_cvt_pk_bf16_f32 v70, v64, v65
	v_pk_mul_f32 v[62:63], v[62:63], v[152:153] op_sel_hi:[1,0]
	v_pk_mul_f32 v[60:61], v[60:61], v[152:153] op_sel_hi:[1,0]
	v_pk_mul_f32 v[58:59], v[58:59], v[152:153] op_sel_hi:[1,0]
	s_and_b64 vcc, exec, s[6:7]
	v_pk_mul_f32 v[64:65], v[56:57], v[152:153] op_sel_hi:[1,0]
	v_cvt_pk_bf16_f32 v71, v66, v67
	s_nop 0
	v_readfirstlane_b32 s84, v72
	v_readfirstlane_b32 s85, v73
	ds_write_b128 v230, v[68:71]
	ds_read_b128 v[240:243], v231
	s_nop 1
	s_waitcnt lgkmcnt(0)
	global_store_dwordx4 v232, v[240:243], s[84:85] offset:256
	s_cbranch_vccnz .LBB0_266
	v_pk_mul_f32 v[56:57], v[62:63], v[62:63]
	v_pk_mul_f32 v[66:67], v[60:61], v[60:61]
	v_mov_b64_e32 v[68:69], s[22:23]
	v_pk_mul_f32 v[70:71], v[58:59], v[58:59]
	v_pk_mul_f32 v[72:73], v[64:65], v[64:65]
	v_pk_fma_f32 v[66:67], v[66:67], s[20:21], v[68:69] op_sel_hi:[1,0,0] neg_lo:[1,0,0] neg_hi:[1,0,0]
	v_pk_fma_f32 v[56:57], v[56:57], s[20:21], v[68:69] op_sel_hi:[1,0,0] neg_lo:[1,0,0] neg_hi:[1,0,0]
	v_pk_fma_f32 v[72:73], v[72:73], s[20:21], v[68:69] op_sel_hi:[1,0,0] neg_lo:[1,0,0] neg_hi:[1,0,0]
	v_pk_fma_f32 v[68:69], v[70:71], s[20:21], v[68:69] op_sel_hi:[1,0,0] neg_lo:[1,0,0] neg_hi:[1,0,0]
	v_pk_mul_f32 v[66:67], v[60:61], v[66:67]
	v_pk_mul_f32 v[56:57], v[62:63], v[56:57]
	v_pk_mul_f32 v[72:73], v[64:65], v[72:73]
	v_pk_mul_f32 v[68:69], v[58:59], v[68:69]
	v_exp_f32_e32 v66, v66
	v_exp_f32_e32 v67, v67
	v_exp_f32_e32 v56, v56
	v_exp_f32_e32 v57, v57
	v_exp_f32_e32 v72, v72
	v_exp_f32_e32 v73, v73
	v_exp_f32_e32 v68, v68
	v_exp_f32_e32 v69, v69
	v_pk_add_f32 v[66:67], v[66:67], 1.0 op_sel_hi:[1,0]
	v_pk_add_f32 v[56:57], v[56:57], 1.0 op_sel_hi:[1,0]
	v_pk_add_f32 v[70:71], v[72:73], 1.0 op_sel_hi:[1,0]
	v_pk_add_f32 v[68:69], v[68:69], 1.0 op_sel_hi:[1,0]
	v_rcp_f32_e32 v66, v66
	v_rcp_f32_e32 v67, v67
	v_rcp_f32_e32 v56, v56
	v_rcp_f32_e32 v57, v57
	v_rcp_f32_e32 v70, v70
	v_rcp_f32_e32 v68, v68
	v_rcp_f32_e32 v69, v69
	v_rcp_f32_e32 v71, v71
	v_pk_mul_f32 v[62:63], v[62:63], v[56:57]
	v_pk_mul_f32 v[60:61], v[60:61], v[66:67]
	v_pk_mul_f32 v[58:59], v[58:59], v[68:69]
	v_pk_mul_f32 v[64:65], v[64:65], v[70:71]
.LBB0_266:
	v_add_u32_e32 v66, 0x80, v146
	v_mov_b64_e32 v[56:57], s[12:13]
	v_mov_b32_e32 v153, v152
	v_mad_i64_i32 v[56:57], s[42:43], v66, s60, v[56:57]
	v_cvt_pk_bf16_f32 v60, v60, v61
	v_cvt_pk_bf16_f32 v61, v62, v63
	v_cvt_pk_bf16_f32 v62, v64, v65
	v_cvt_pk_bf16_f32 v63, v58, v59
	v_mov_b32_e32 v58, v152
	v_mov_b32_e32 v59, v152
	v_lshl_add_u64 v[56:57], v[120:121], 1, v[56:57]
	v_pk_mul_f32 v[54:55], v[54:55], v[58:59]
	v_pk_mul_f32 v[52:53], v[52:53], v[152:153]
	v_pk_mul_f32 v[50:51], v[50:51], v[58:59]
	s_and_b64 vcc, exec, s[6:7]
	v_pk_mul_f32 v[48:49], v[48:49], v[152:153]
	s_nop 0
	v_readfirstlane_b32 s82, v56
	v_readfirstlane_b32 s83, v57
	ds_write_b128 v230, v[60:63]
	ds_read_b128 v[236:239], v231
	s_nop 1
	s_waitcnt lgkmcnt(0)
	global_store_dwordx4 v232, v[236:239], s[82:83]
	s_cbranch_vccnz .LBB0_268
	v_pk_mul_f32 v[58:59], v[54:55], v[54:55]
	v_pk_mul_f32 v[60:61], v[52:53], v[52:53]
	v_mov_b64_e32 v[62:63], s[22:23]
	v_pk_mul_f32 v[64:65], v[50:51], v[50:51]
	v_pk_mul_f32 v[66:67], v[48:49], v[48:49]
	v_pk_fma_f32 v[60:61], v[60:61], s[20:21], v[62:63] op_sel_hi:[1,0,0] neg_lo:[1,0,0] neg_hi:[1,0,0]
	v_pk_fma_f32 v[58:59], v[58:59], s[20:21], v[62:63] op_sel_hi:[1,0,0] neg_lo:[1,0,0] neg_hi:[1,0,0]
	v_pk_fma_f32 v[66:67], v[66:67], s[20:21], v[62:63] op_sel_hi:[1,0,0] neg_lo:[1,0,0] neg_hi:[1,0,0]
	v_pk_fma_f32 v[62:63], v[64:65], s[20:21], v[62:63] op_sel_hi:[1,0,0] neg_lo:[1,0,0] neg_hi:[1,0,0]
	v_pk_mul_f32 v[60:61], v[52:53], v[60:61]
	v_pk_mul_f32 v[58:59], v[54:55], v[58:59]
	v_pk_mul_f32 v[66:67], v[48:49], v[66:67]
	v_pk_mul_f32 v[62:63], v[50:51], v[62:63]
	v_exp_f32_e32 v60, v60
	v_exp_f32_e32 v61, v61
	v_exp_f32_e32 v58, v58
	v_exp_f32_e32 v59, v59
	v_exp_f32_e32 v66, v66
	v_exp_f32_e32 v67, v67
	v_exp_f32_e32 v62, v62
	v_exp_f32_e32 v63, v63
	v_pk_add_f32 v[60:61], v[60:61], 1.0 op_sel_hi:[1,0]
	v_pk_add_f32 v[58:59], v[58:59], 1.0 op_sel_hi:[1,0]
	v_pk_add_f32 v[64:65], v[66:67], 1.0 op_sel_hi:[1,0]
	v_pk_add_f32 v[62:63], v[62:63], 1.0 op_sel_hi:[1,0]
	v_rcp_f32_e32 v60, v60
	v_rcp_f32_e32 v61, v61
	v_rcp_f32_e32 v58, v58
	v_rcp_f32_e32 v59, v59
	v_rcp_f32_e32 v64, v64
	v_rcp_f32_e32 v62, v62
	v_rcp_f32_e32 v63, v63
	v_rcp_f32_e32 v65, v65
	v_pk_mul_f32 v[54:55], v[54:55], v[58:59]
	v_pk_mul_f32 v[52:53], v[52:53], v[60:61]
	v_pk_mul_f32 v[50:51], v[50:51], v[62:63]
	v_pk_mul_f32 v[48:49], v[48:49], v[64:65]
.LBB0_268:
	v_cvt_pk_bf16_f32 v52, v52, v53
	v_cvt_pk_bf16_f32 v53, v54, v55
	s_nop 0
	v_cvt_pk_bf16_f32 v54, v48, v49
	v_pk_mul_f32 v[46:47], v[46:47], v[150:151] op_sel_hi:[1,0]
	v_pk_mul_f32 v[44:45], v[44:45], v[150:151] op_sel_hi:[1,0]
	v_pk_mul_f32 v[42:43], v[42:43], v[150:151] op_sel_hi:[1,0]
	s_and_b64 vcc, exec, s[6:7]
	v_pk_mul_f32 v[48:49], v[40:41], v[150:151] op_sel_hi:[1,0]
	v_cvt_pk_bf16_f32 v55, v50, v51
	s_nop 0
	v_readfirstlane_b32 s84, v56
	v_readfirstlane_b32 s85, v57
	ds_write_b128 v230, v[52:55]
	ds_read_b128 v[240:243], v231
	s_nop 1
	s_waitcnt lgkmcnt(0)
	global_store_dwordx4 v232, v[240:243], s[84:85] offset:256
	s_cbranch_vccnz .LBB0_270
	v_pk_mul_f32 v[40:41], v[46:47], v[46:47]
	v_pk_mul_f32 v[50:51], v[44:45], v[44:45]
	v_mov_b64_e32 v[52:53], s[22:23]
	v_pk_mul_f32 v[54:55], v[42:43], v[42:43]
	v_pk_mul_f32 v[56:57], v[48:49], v[48:49]
	v_pk_fma_f32 v[50:51], v[50:51], s[20:21], v[52:53] op_sel_hi:[1,0,0] neg_lo:[1,0,0] neg_hi:[1,0,0]
	v_pk_fma_f32 v[40:41], v[40:41], s[20:21], v[52:53] op_sel_hi:[1,0,0] neg_lo:[1,0,0] neg_hi:[1,0,0]
	v_pk_fma_f32 v[56:57], v[56:57], s[20:21], v[52:53] op_sel_hi:[1,0,0] neg_lo:[1,0,0] neg_hi:[1,0,0]
	v_pk_fma_f32 v[52:53], v[54:55], s[20:21], v[52:53] op_sel_hi:[1,0,0] neg_lo:[1,0,0] neg_hi:[1,0,0]
	v_pk_mul_f32 v[50:51], v[44:45], v[50:51]
	v_pk_mul_f32 v[40:41], v[46:47], v[40:41]
	v_pk_mul_f32 v[56:57], v[48:49], v[56:57]
	v_pk_mul_f32 v[52:53], v[42:43], v[52:53]
	v_exp_f32_e32 v50, v50
	v_exp_f32_e32 v51, v51
	v_exp_f32_e32 v40, v40
	v_exp_f32_e32 v41, v41
	v_exp_f32_e32 v56, v56
	v_exp_f32_e32 v57, v57
	v_exp_f32_e32 v52, v52
	v_exp_f32_e32 v53, v53
	v_pk_add_f32 v[50:51], v[50:51], 1.0 op_sel_hi:[1,0]
	v_pk_add_f32 v[40:41], v[40:41], 1.0 op_sel_hi:[1,0]
	v_pk_add_f32 v[54:55], v[56:57], 1.0 op_sel_hi:[1,0]
	v_pk_add_f32 v[52:53], v[52:53], 1.0 op_sel_hi:[1,0]
	v_rcp_f32_e32 v50, v50
	v_rcp_f32_e32 v51, v51
	v_rcp_f32_e32 v40, v40
	v_rcp_f32_e32 v41, v41
	v_rcp_f32_e32 v54, v54
	v_rcp_f32_e32 v52, v52
	v_rcp_f32_e32 v53, v53
	v_rcp_f32_e32 v55, v55
	v_pk_mul_f32 v[46:47], v[46:47], v[40:41]
	v_pk_mul_f32 v[44:45], v[44:45], v[50:51]
	v_pk_mul_f32 v[42:43], v[42:43], v[52:53]
	v_pk_mul_f32 v[48:49], v[48:49], v[54:55]
.LBB0_270:
	v_add_u32_e32 v50, 0x90, v146
	v_mov_b64_e32 v[40:41], s[12:13]
	v_mov_b32_e32 v151, v150
	v_mad_i64_i32 v[40:41], s[42:43], v50, s60, v[40:41]
	v_cvt_pk_bf16_f32 v44, v44, v45
	v_cvt_pk_bf16_f32 v45, v46, v47
	v_cvt_pk_bf16_f32 v46, v48, v49
	v_cvt_pk_bf16_f32 v47, v42, v43
	v_mov_b32_e32 v42, v150
	v_mov_b32_e32 v43, v150
	v_lshl_add_u64 v[40:41], v[120:121], 1, v[40:41]
	v_pk_mul_f32 v[38:39], v[38:39], v[42:43]
	v_pk_mul_f32 v[36:37], v[36:37], v[150:151]
	v_pk_mul_f32 v[34:35], v[34:35], v[42:43]
	s_and_b64 vcc, exec, s[6:7]
	v_pk_mul_f32 v[32:33], v[32:33], v[150:151]
	s_nop 0
	v_readfirstlane_b32 s82, v40
	v_readfirstlane_b32 s83, v41
	ds_write_b128 v230, v[44:47]
	ds_read_b128 v[236:239], v231
	s_nop 1
	s_waitcnt lgkmcnt(0)
	global_store_dwordx4 v232, v[236:239], s[82:83]
	s_cbranch_vccnz .LBB0_272
	v_pk_mul_f32 v[42:43], v[38:39], v[38:39]
	v_pk_mul_f32 v[44:45], v[36:37], v[36:37]
	v_mov_b64_e32 v[46:47], s[22:23]
	v_pk_mul_f32 v[48:49], v[34:35], v[34:35]
	v_pk_mul_f32 v[50:51], v[32:33], v[32:33]
	v_pk_fma_f32 v[44:45], v[44:45], s[20:21], v[46:47] op_sel_hi:[1,0,0] neg_lo:[1,0,0] neg_hi:[1,0,0]
	v_pk_fma_f32 v[42:43], v[42:43], s[20:21], v[46:47] op_sel_hi:[1,0,0] neg_lo:[1,0,0] neg_hi:[1,0,0]
	v_pk_fma_f32 v[50:51], v[50:51], s[20:21], v[46:47] op_sel_hi:[1,0,0] neg_lo:[1,0,0] neg_hi:[1,0,0]
	v_pk_fma_f32 v[46:47], v[48:49], s[20:21], v[46:47] op_sel_hi:[1,0,0] neg_lo:[1,0,0] neg_hi:[1,0,0]
	v_pk_mul_f32 v[44:45], v[36:37], v[44:45]
	v_pk_mul_f32 v[42:43], v[38:39], v[42:43]
	v_pk_mul_f32 v[50:51], v[32:33], v[50:51]
	v_pk_mul_f32 v[46:47], v[34:35], v[46:47]
	v_exp_f32_e32 v44, v44
	v_exp_f32_e32 v45, v45
	v_exp_f32_e32 v42, v42
	v_exp_f32_e32 v43, v43
	v_exp_f32_e32 v50, v50
	v_exp_f32_e32 v51, v51
	v_exp_f32_e32 v46, v46
	v_exp_f32_e32 v47, v47
	v_pk_add_f32 v[44:45], v[44:45], 1.0 op_sel_hi:[1,0]
	v_pk_add_f32 v[42:43], v[42:43], 1.0 op_sel_hi:[1,0]
	v_pk_add_f32 v[48:49], v[50:51], 1.0 op_sel_hi:[1,0]
	v_pk_add_f32 v[46:47], v[46:47], 1.0 op_sel_hi:[1,0]
	v_rcp_f32_e32 v44, v44
	v_rcp_f32_e32 v45, v45
	v_rcp_f32_e32 v42, v42
	v_rcp_f32_e32 v43, v43
	v_rcp_f32_e32 v48, v48
	v_rcp_f32_e32 v46, v46
	v_rcp_f32_e32 v47, v47
	v_rcp_f32_e32 v49, v49
	v_pk_mul_f32 v[38:39], v[38:39], v[42:43]
	v_pk_mul_f32 v[36:37], v[36:37], v[44:45]
	v_pk_mul_f32 v[34:35], v[34:35], v[46:47]
	v_pk_mul_f32 v[32:33], v[32:33], v[48:49]
.LBB0_272:
	v_cvt_pk_bf16_f32 v36, v36, v37
	v_cvt_pk_bf16_f32 v37, v38, v39
	s_nop 0
	v_cvt_pk_bf16_f32 v38, v32, v33
	v_pk_mul_f32 v[30:31], v[30:31], v[148:149] op_sel_hi:[1,0]
	v_pk_mul_f32 v[28:29], v[28:29], v[148:149] op_sel_hi:[1,0]
	v_pk_mul_f32 v[26:27], v[26:27], v[148:149] op_sel_hi:[1,0]
	s_and_b64 vcc, exec, s[6:7]
	v_pk_mul_f32 v[32:33], v[24:25], v[148:149] op_sel_hi:[1,0]
	v_cvt_pk_bf16_f32 v39, v34, v35
	s_nop 0
	v_readfirstlane_b32 s84, v40
	v_readfirstlane_b32 s85, v41
	ds_write_b128 v230, v[36:39]
	ds_read_b128 v[240:243], v231
	s_nop 1
	s_waitcnt lgkmcnt(0)
	global_store_dwordx4 v232, v[240:243], s[84:85] offset:256
	s_cbranch_vccnz .LBB0_274
	v_pk_mul_f32 v[24:25], v[30:31], v[30:31]
	v_pk_mul_f32 v[34:35], v[28:29], v[28:29]
	v_mov_b64_e32 v[36:37], s[22:23]
	v_pk_mul_f32 v[38:39], v[26:27], v[26:27]
	v_pk_mul_f32 v[40:41], v[32:33], v[32:33]
	v_pk_fma_f32 v[34:35], v[34:35], s[20:21], v[36:37] op_sel_hi:[1,0,0] neg_lo:[1,0,0] neg_hi:[1,0,0]
	v_pk_fma_f32 v[24:25], v[24:25], s[20:21], v[36:37] op_sel_hi:[1,0,0] neg_lo:[1,0,0] neg_hi:[1,0,0]
	v_pk_fma_f32 v[40:41], v[40:41], s[20:21], v[36:37] op_sel_hi:[1,0,0] neg_lo:[1,0,0] neg_hi:[1,0,0]
	v_pk_fma_f32 v[36:37], v[38:39], s[20:21], v[36:37] op_sel_hi:[1,0,0] neg_lo:[1,0,0] neg_hi:[1,0,0]
	v_pk_mul_f32 v[34:35], v[28:29], v[34:35]
	v_pk_mul_f32 v[24:25], v[30:31], v[24:25]
	v_pk_mul_f32 v[40:41], v[32:33], v[40:41]
	v_pk_mul_f32 v[36:37], v[26:27], v[36:37]
	v_exp_f32_e32 v34, v34
	v_exp_f32_e32 v35, v35
	v_exp_f32_e32 v24, v24
	v_exp_f32_e32 v25, v25
	v_exp_f32_e32 v40, v40
	v_exp_f32_e32 v41, v41
	v_exp_f32_e32 v36, v36
	v_exp_f32_e32 v37, v37
	v_pk_add_f32 v[34:35], v[34:35], 1.0 op_sel_hi:[1,0]
	v_pk_add_f32 v[24:25], v[24:25], 1.0 op_sel_hi:[1,0]
	v_pk_add_f32 v[38:39], v[40:41], 1.0 op_sel_hi:[1,0]
	v_pk_add_f32 v[36:37], v[36:37], 1.0 op_sel_hi:[1,0]
	v_rcp_f32_e32 v34, v34
	v_rcp_f32_e32 v35, v35
	v_rcp_f32_e32 v24, v24
	v_rcp_f32_e32 v25, v25
	v_rcp_f32_e32 v38, v38
	v_rcp_f32_e32 v36, v36
	v_rcp_f32_e32 v37, v37
	v_rcp_f32_e32 v39, v39
	v_pk_mul_f32 v[30:31], v[30:31], v[24:25]
	v_pk_mul_f32 v[28:29], v[28:29], v[34:35]
	v_pk_mul_f32 v[26:27], v[26:27], v[36:37]
	v_pk_mul_f32 v[32:33], v[32:33], v[38:39]
.LBB0_274:
	v_add_u32_e32 v34, 0xa0, v146
	v_mov_b64_e32 v[24:25], s[12:13]
	v_mov_b32_e32 v149, v148
	v_mad_i64_i32 v[24:25], s[42:43], v34, s60, v[24:25]
	v_cvt_pk_bf16_f32 v28, v28, v29
	v_cvt_pk_bf16_f32 v29, v30, v31
	v_cvt_pk_bf16_f32 v30, v32, v33
	v_cvt_pk_bf16_f32 v31, v26, v27
	v_mov_b32_e32 v26, v148
	v_mov_b32_e32 v27, v148
	v_lshl_add_u64 v[24:25], v[120:121], 1, v[24:25]
	v_pk_mul_f32 v[22:23], v[22:23], v[26:27]
	v_pk_mul_f32 v[20:21], v[20:21], v[148:149]
	v_pk_mul_f32 v[18:19], v[18:19], v[26:27]
	s_and_b64 vcc, exec, s[6:7]
	v_pk_mul_f32 v[16:17], v[16:17], v[148:149]
	s_nop 0
	v_readfirstlane_b32 s82, v24
	v_readfirstlane_b32 s83, v25
	ds_write_b128 v230, v[28:31]
	ds_read_b128 v[236:239], v231
	s_nop 1
	s_waitcnt lgkmcnt(0)
	global_store_dwordx4 v232, v[236:239], s[82:83]
	s_cbranch_vccnz .LBB0_276
	v_pk_mul_f32 v[26:27], v[22:23], v[22:23]
	v_pk_mul_f32 v[28:29], v[20:21], v[20:21]
	v_mov_b64_e32 v[30:31], s[22:23]
	v_pk_mul_f32 v[32:33], v[18:19], v[18:19]
	v_pk_mul_f32 v[34:35], v[16:17], v[16:17]
	v_pk_fma_f32 v[28:29], v[28:29], s[20:21], v[30:31] op_sel_hi:[1,0,0] neg_lo:[1,0,0] neg_hi:[1,0,0]
	v_pk_fma_f32 v[26:27], v[26:27], s[20:21], v[30:31] op_sel_hi:[1,0,0] neg_lo:[1,0,0] neg_hi:[1,0,0]
	v_pk_fma_f32 v[34:35], v[34:35], s[20:21], v[30:31] op_sel_hi:[1,0,0] neg_lo:[1,0,0] neg_hi:[1,0,0]
	v_pk_fma_f32 v[30:31], v[32:33], s[20:21], v[30:31] op_sel_hi:[1,0,0] neg_lo:[1,0,0] neg_hi:[1,0,0]
	v_pk_mul_f32 v[28:29], v[20:21], v[28:29]
	v_pk_mul_f32 v[26:27], v[22:23], v[26:27]
	v_pk_mul_f32 v[34:35], v[16:17], v[34:35]
	v_pk_mul_f32 v[30:31], v[18:19], v[30:31]
	v_exp_f32_e32 v28, v28
	v_exp_f32_e32 v29, v29
	v_exp_f32_e32 v26, v26
	v_exp_f32_e32 v27, v27
	v_exp_f32_e32 v34, v34
	v_exp_f32_e32 v35, v35
	v_exp_f32_e32 v30, v30
	v_exp_f32_e32 v31, v31
	v_pk_add_f32 v[28:29], v[28:29], 1.0 op_sel_hi:[1,0]
	v_pk_add_f32 v[26:27], v[26:27], 1.0 op_sel_hi:[1,0]
	v_pk_add_f32 v[32:33], v[34:35], 1.0 op_sel_hi:[1,0]
	v_pk_add_f32 v[30:31], v[30:31], 1.0 op_sel_hi:[1,0]
	v_rcp_f32_e32 v28, v28
	v_rcp_f32_e32 v29, v29
	v_rcp_f32_e32 v26, v26
	v_rcp_f32_e32 v27, v27
	v_rcp_f32_e32 v32, v32
	v_rcp_f32_e32 v30, v30
	v_rcp_f32_e32 v31, v31
	v_rcp_f32_e32 v33, v33
	v_pk_mul_f32 v[22:23], v[22:23], v[26:27]
	v_pk_mul_f32 v[20:21], v[20:21], v[28:29]
	v_pk_mul_f32 v[18:19], v[18:19], v[30:31]
	v_pk_mul_f32 v[16:17], v[16:17], v[32:33]
.LBB0_276:
	v_cvt_pk_bf16_f32 v20, v20, v21
	v_cvt_pk_bf16_f32 v21, v22, v23
	s_nop 0
	v_cvt_pk_bf16_f32 v22, v16, v17
	v_pk_mul_f32 v[14:15], v[14:15], v[144:145] op_sel_hi:[1,0]
	v_pk_mul_f32 v[12:13], v[12:13], v[144:145] op_sel_hi:[1,0]
	v_pk_mul_f32 v[10:11], v[10:11], v[144:145] op_sel_hi:[1,0]
	s_and_b64 vcc, exec, s[6:7]
	v_pk_mul_f32 v[16:17], v[8:9], v[144:145] op_sel_hi:[1,0]
	v_cvt_pk_bf16_f32 v23, v18, v19
	s_nop 0
	v_readfirstlane_b32 s84, v24
	v_readfirstlane_b32 s85, v25
	ds_write_b128 v230, v[20:23]
	ds_read_b128 v[240:243], v231
	s_nop 1
	s_waitcnt lgkmcnt(0)
	global_store_dwordx4 v232, v[240:243], s[84:85] offset:256
	s_cbranch_vccnz .LBB0_278
	v_pk_mul_f32 v[8:9], v[14:15], v[14:15]
	v_pk_mul_f32 v[18:19], v[12:13], v[12:13]
	v_mov_b64_e32 v[20:21], s[22:23]
	v_pk_mul_f32 v[22:23], v[10:11], v[10:11]
	v_pk_mul_f32 v[24:25], v[16:17], v[16:17]
	v_pk_fma_f32 v[18:19], v[18:19], s[20:21], v[20:21] op_sel_hi:[1,0,0] neg_lo:[1,0,0] neg_hi:[1,0,0]
	v_pk_fma_f32 v[8:9], v[8:9], s[20:21], v[20:21] op_sel_hi:[1,0,0] neg_lo:[1,0,0] neg_hi:[1,0,0]
	v_pk_fma_f32 v[24:25], v[24:25], s[20:21], v[20:21] op_sel_hi:[1,0,0] neg_lo:[1,0,0] neg_hi:[1,0,0]
	v_pk_fma_f32 v[20:21], v[22:23], s[20:21], v[20:21] op_sel_hi:[1,0,0] neg_lo:[1,0,0] neg_hi:[1,0,0]
	v_pk_mul_f32 v[18:19], v[12:13], v[18:19]
	v_pk_mul_f32 v[8:9], v[14:15], v[8:9]
	v_pk_mul_f32 v[24:25], v[16:17], v[24:25]
	v_pk_mul_f32 v[20:21], v[10:11], v[20:21]
	v_exp_f32_e32 v18, v18
	v_exp_f32_e32 v19, v19
	v_exp_f32_e32 v8, v8
	v_exp_f32_e32 v9, v9
	v_exp_f32_e32 v24, v24
	v_exp_f32_e32 v25, v25
	v_exp_f32_e32 v20, v20
	v_exp_f32_e32 v21, v21
	v_pk_add_f32 v[18:19], v[18:19], 1.0 op_sel_hi:[1,0]
	v_pk_add_f32 v[8:9], v[8:9], 1.0 op_sel_hi:[1,0]
	v_pk_add_f32 v[22:23], v[24:25], 1.0 op_sel_hi:[1,0]
	v_pk_add_f32 v[20:21], v[20:21], 1.0 op_sel_hi:[1,0]
	v_rcp_f32_e32 v18, v18
	v_rcp_f32_e32 v19, v19
	v_rcp_f32_e32 v8, v8
	v_rcp_f32_e32 v9, v9
	v_rcp_f32_e32 v22, v22
	v_rcp_f32_e32 v20, v20
	v_rcp_f32_e32 v21, v21
	v_rcp_f32_e32 v23, v23
	v_pk_mul_f32 v[14:15], v[14:15], v[8:9]
	v_pk_mul_f32 v[12:13], v[12:13], v[18:19]
	v_pk_mul_f32 v[10:11], v[10:11], v[20:21]
	v_pk_mul_f32 v[16:17], v[16:17], v[22:23]
.LBB0_278:
	v_add_u32_e32 v18, 0xb0, v146
	v_mov_b64_e32 v[8:9], s[12:13]
	v_mov_b32_e32 v145, v144
	v_mad_i64_i32 v[8:9], s[42:43], v18, s60, v[8:9]
	v_cvt_pk_bf16_f32 v12, v12, v13
	v_cvt_pk_bf16_f32 v13, v14, v15
	v_cvt_pk_bf16_f32 v14, v16, v17
	v_cvt_pk_bf16_f32 v15, v10, v11
	v_mov_b32_e32 v10, v144
	v_mov_b32_e32 v11, v144
	v_lshl_add_u64 v[8:9], v[120:121], 1, v[8:9]
	v_pk_mul_f32 v[6:7], v[6:7], v[10:11]
	v_pk_mul_f32 v[4:5], v[4:5], v[144:145]
	v_pk_mul_f32 v[2:3], v[2:3], v[10:11]
	s_and_b64 vcc, exec, s[6:7]
	v_pk_mul_f32 v[0:1], v[0:1], v[144:145]
	s_nop 0
	v_readfirstlane_b32 s82, v8
	v_readfirstlane_b32 s83, v9
	ds_write_b128 v230, v[12:15]
	ds_read_b128 v[236:239], v231
	s_nop 1
	s_waitcnt lgkmcnt(0)
	global_store_dwordx4 v232, v[236:239], s[82:83]
	s_cbranch_vccnz .LBB0_280
	v_pk_mul_f32 v[10:11], v[6:7], v[6:7]
	v_pk_mul_f32 v[12:13], v[4:5], v[4:5]
	v_mov_b64_e32 v[14:15], s[22:23]
	v_pk_mul_f32 v[16:17], v[2:3], v[2:3]
	v_pk_mul_f32 v[18:19], v[0:1], v[0:1]
	v_pk_fma_f32 v[12:13], v[12:13], s[20:21], v[14:15] op_sel_hi:[1,0,0] neg_lo:[1,0,0] neg_hi:[1,0,0]
	v_pk_fma_f32 v[10:11], v[10:11], s[20:21], v[14:15] op_sel_hi:[1,0,0] neg_lo:[1,0,0] neg_hi:[1,0,0]
	v_pk_fma_f32 v[18:19], v[18:19], s[20:21], v[14:15] op_sel_hi:[1,0,0] neg_lo:[1,0,0] neg_hi:[1,0,0]
	v_pk_fma_f32 v[14:15], v[16:17], s[20:21], v[14:15] op_sel_hi:[1,0,0] neg_lo:[1,0,0] neg_hi:[1,0,0]
	v_pk_mul_f32 v[12:13], v[4:5], v[12:13]
	v_pk_mul_f32 v[10:11], v[6:7], v[10:11]
	v_pk_mul_f32 v[18:19], v[0:1], v[18:19]
	v_pk_mul_f32 v[14:15], v[2:3], v[14:15]
	v_exp_f32_e32 v12, v12
	v_exp_f32_e32 v13, v13
	v_exp_f32_e32 v10, v10
	v_exp_f32_e32 v11, v11
	v_exp_f32_e32 v18, v18
	v_exp_f32_e32 v19, v19
	v_exp_f32_e32 v14, v14
	v_exp_f32_e32 v15, v15
	v_pk_add_f32 v[12:13], v[12:13], 1.0 op_sel_hi:[1,0]
	v_pk_add_f32 v[10:11], v[10:11], 1.0 op_sel_hi:[1,0]
	v_pk_add_f32 v[16:17], v[18:19], 1.0 op_sel_hi:[1,0]
	v_pk_add_f32 v[14:15], v[14:15], 1.0 op_sel_hi:[1,0]
	v_rcp_f32_e32 v12, v12
	v_rcp_f32_e32 v13, v13
	v_rcp_f32_e32 v10, v10
	v_rcp_f32_e32 v11, v11
	v_rcp_f32_e32 v16, v16
	v_rcp_f32_e32 v14, v14
	v_rcp_f32_e32 v15, v15
	v_rcp_f32_e32 v17, v17
	v_pk_mul_f32 v[6:7], v[6:7], v[10:11]
	v_pk_mul_f32 v[4:5], v[4:5], v[12:13]
	v_pk_mul_f32 v[2:3], v[2:3], v[14:15]
	v_pk_mul_f32 v[0:1], v[0:1], v[16:17]
.LBB0_280:
	s_andn2_b64 vcc, exec, s[4:5]
	s_mov_b64 s[4:5], -1
	v_cvt_pk_bf16_f32 v4, v4, v5
	v_cvt_pk_bf16_f32 v5, v6, v7
	v_cvt_pk_bf16_f32 v6, v0, v1
	v_cvt_pk_bf16_f32 v7, v2, v3
	s_nop 0
	v_readfirstlane_b32 s84, v8
	v_readfirstlane_b32 s85, v9
	ds_write_b128 v230, v[4:7]
	ds_read_b128 v[240:243], v231
	s_nop 1
	s_waitcnt lgkmcnt(0)
	global_store_dwordx4 v232, v[240:243], s[84:85] offset:256
	s_cbranch_vccnz .LBB0_241
	s_andn2_b64 vcc, exec, s[10:11]
	s_cbranch_vccnz .LBB0_240
	s_barrier
	s_branch .LBB0_240

.LBB0_310:
	v_lshl_add_u32 v146, s65, 8, v140
	v_lshl_or_b32 v148, s68, 8, v142
	v_ashrrev_i32_e32 v147, 31, v146
	v_ashrrev_i32_e32 v149, 31, v148
	v_lshlrev_b64 v[150:151], 11, v[146:147]
	v_lshl_add_u64 v[150:151], s[14:15], 0, v[150:151]
	v_lshlrev_b64 v[148:149], 1, v[148:149]
	v_lshl_add_u64 v[150:151], v[150:151], 0, v[148:149]
	v_cvt_pk_bf16_f32 v120, v120, v121
	v_cvt_pk_bf16_f32 v121, v122, v123
	v_cvt_pk_bf16_f32 v122, v124, v125
	v_cvt_pk_bf16_f32 v123, v126, v127
	s_nop 0
	v_readfirstlane_b32 s82, v150
	v_readfirstlane_b32 s83, v151
	ds_write_b128 v230, v[120:123]
	ds_read_b128 v[236:239], v231
	s_nop 1
	s_waitcnt lgkmcnt(0)
	global_store_dwordx4 v233, v[236:239], s[82:83]
	v_cvt_pk_bf16_f32 v116, v116, v117
	v_cvt_pk_bf16_f32 v117, v118, v119
	v_cvt_pk_bf16_f32 v118, v112, v113
	v_or_b32_e32 v112, 16, v146
	v_ashrrev_i32_e32 v113, 31, v112
	v_lshlrev_b64 v[112:113], 11, v[112:113]
	v_lshl_add_u64 v[112:113], s[14:15], 0, v[112:113]
	v_lshl_add_u64 v[112:113], v[112:113], 0, v[148:149]
	v_cvt_pk_bf16_f32 v119, v114, v115
	s_nop 0
	v_readfirstlane_b32 s84, v150
	v_readfirstlane_b32 s85, v151
	ds_write_b128 v230, v[116:119]
	ds_read_b128 v[240:243], v231
	s_nop 1
	s_waitcnt lgkmcnt(0)
	global_store_dwordx4 v233, v[240:243], s[84:85] offset:256
	v_cvt_pk_bf16_f32 v108, v108, v109
	v_cvt_pk_bf16_f32 v109, v110, v111
	v_cvt_pk_bf16_f32 v110, v104, v105
	v_cvt_pk_bf16_f32 v111, v106, v107
	s_nop 0
	v_readfirstlane_b32 s82, v112
	v_readfirstlane_b32 s83, v113
	ds_write_b128 v230, v[108:111]
	ds_read_b128 v[236:239], v231
	s_nop 1
	s_waitcnt lgkmcnt(0)
	global_store_dwordx4 v233, v[236:239], s[82:83]
	v_cvt_pk_bf16_f32 v100, v100, v101
	v_cvt_pk_bf16_f32 v101, v102, v103
	v_cvt_pk_bf16_f32 v102, v96, v97
	v_or_b32_e32 v96, 32, v146
	v_ashrrev_i32_e32 v97, 31, v96
	v_lshlrev_b64 v[96:97], 11, v[96:97]
	v_lshl_add_u64 v[96:97], s[14:15], 0, v[96:97]
	v_lshl_add_u64 v[96:97], v[96:97], 0, v[148:149]
	v_cvt_pk_bf16_f32 v103, v98, v99
	s_nop 0
	v_readfirstlane_b32 s84, v112
	v_readfirstlane_b32 s85, v113
	ds_write_b128 v230, v[100:103]
	ds_read_b128 v[240:243], v231
	s_nop 1
	s_waitcnt lgkmcnt(0)
	global_store_dwordx4 v233, v[240:243], s[84:85] offset:256
	v_cvt_pk_bf16_f32 v92, v92, v93
	v_cvt_pk_bf16_f32 v93, v94, v95
	v_cvt_pk_bf16_f32 v94, v88, v89
	v_cvt_pk_bf16_f32 v95, v90, v91
	s_nop 0
	v_readfirstlane_b32 s82, v96
	v_readfirstlane_b32 s83, v97
	ds_write_b128 v230, v[92:95]
	ds_read_b128 v[236:239], v231
	s_nop 1
	s_waitcnt lgkmcnt(0)
	global_store_dwordx4 v233, v[236:239], s[82:83]
	v_cvt_pk_bf16_f32 v84, v84, v85
	v_cvt_pk_bf16_f32 v85, v86, v87
	v_cvt_pk_bf16_f32 v86, v80, v81
	v_or_b32_e32 v80, 48, v146
	v_ashrrev_i32_e32 v81, 31, v80
	v_lshlrev_b64 v[80:81], 11, v[80:81]
	v_lshl_add_u64 v[80:81], s[14:15], 0, v[80:81]
	v_lshl_add_u64 v[80:81], v[80:81], 0, v[148:149]
	v_cvt_pk_bf16_f32 v87, v82, v83
	s_nop 0
	v_readfirstlane_b32 s84, v96
	v_readfirstlane_b32 s85, v97
	ds_write_b128 v230, v[84:87]
	ds_read_b128 v[240:243], v231
	s_nop 1
	s_waitcnt lgkmcnt(0)
	global_store_dwordx4 v233, v[240:243], s[84:85] offset:256
	v_cvt_pk_bf16_f32 v76, v76, v77
	v_cvt_pk_bf16_f32 v77, v78, v79
	v_cvt_pk_bf16_f32 v78, v72, v73
	v_cvt_pk_bf16_f32 v79, v74, v75
	s_nop 0
	v_readfirstlane_b32 s82, v80
	v_readfirstlane_b32 s83, v81
	ds_write_b128 v230, v[76:79]
	ds_read_b128 v[236:239], v231
	s_nop 1
	s_waitcnt lgkmcnt(0)
	global_store_dwordx4 v233, v[236:239], s[82:83]
	v_cvt_pk_bf16_f32 v68, v68, v69
	v_cvt_pk_bf16_f32 v69, v70, v71
	v_cvt_pk_bf16_f32 v70, v64, v65
	v_cvt_pk_bf16_f32 v71, v66, v67
	s_nop 0
	v_readfirstlane_b32 s84, v80
	v_readfirstlane_b32 s85, v81
	ds_write_b128 v230, v[68:71]
	ds_read_b128 v[240:243], v231
	s_nop 1
	s_waitcnt lgkmcnt(0)
	global_store_dwordx4 v233, v[240:243], s[84:85] offset:256
	v_cvt_pk_bf16_f32 v60, v60, v61
	v_cvt_pk_bf16_f32 v61, v62, v63
	v_cvt_pk_bf16_f32 v62, v56, v57
	v_add_co_u32_e32 v56, vcc, s62, v150
	v_lshl_add_u64 v[64:65], v[150:151], 0, s[22:23]
	s_nop 0
	v_addc_co_u32_e32 v57, vcc, 0, v151, vcc
	v_cvt_pk_bf16_f32 v63, v58, v59
	s_nop 0
	v_readfirstlane_b32 s82, v56
	v_readfirstlane_b32 s83, v57
	ds_write_b128 v230, v[60:63]
	ds_read_b128 v[236:239], v231
	s_nop 1
	s_waitcnt lgkmcnt(0)
	global_store_dwordx4 v233, v[236:239], s[82:83]
	v_cvt_pk_bf16_f32 v52, v52, v53
	v_cvt_pk_bf16_f32 v53, v54, v55
	v_cvt_pk_bf16_f32 v54, v48, v49
	v_cvt_pk_bf16_f32 v55, v50, v51
	s_nop 0
	v_readfirstlane_b32 s84, v64
	v_readfirstlane_b32 s85, v65
	ds_write_b128 v230, v[52:55]
	ds_read_b128 v[240:243], v231
	s_nop 1
	s_waitcnt lgkmcnt(0)
	global_store_dwordx4 v233, v[240:243], s[84:85] offset:256
	v_cvt_pk_bf16_f32 v44, v44, v45
	v_cvt_pk_bf16_f32 v45, v46, v47
	v_cvt_pk_bf16_f32 v46, v40, v41
	v_add_co_u32_e32 v40, vcc, s63, v150
	v_lshl_add_u64 v[48:49], v[150:151], 0, s[24:25]
	s_nop 0
	v_addc_co_u32_e32 v41, vcc, 0, v151, vcc
	v_cvt_pk_bf16_f32 v47, v42, v43
	s_nop 0
	v_readfirstlane_b32 s82, v40
	v_readfirstlane_b32 s83, v41
	ds_write_b128 v230, v[44:47]
	ds_read_b128 v[236:239], v231
	s_nop 1
	s_waitcnt lgkmcnt(0)
	global_store_dwordx4 v233, v[236:239], s[82:83]
	v_cvt_pk_bf16_f32 v36, v36, v37
	v_cvt_pk_bf16_f32 v37, v38, v39
	v_cvt_pk_bf16_f32 v38, v32, v33
	v_cvt_pk_bf16_f32 v39, v34, v35
	s_nop 0
	v_readfirstlane_b32 s84, v48
	v_readfirstlane_b32 s85, v49
	ds_write_b128 v230, v[36:39]
	ds_read_b128 v[240:243], v231
	s_nop 1
	s_waitcnt lgkmcnt(0)
	global_store_dwordx4 v233, v[240:243], s[84:85] offset:256
	v_cvt_pk_bf16_f32 v28, v28, v29
	v_cvt_pk_bf16_f32 v29, v30, v31
	v_cvt_pk_bf16_f32 v30, v24, v25
	v_add_co_u32_e32 v24, vcc, s64, v150
	v_lshl_add_u64 v[32:33], v[150:151], 0, s[36:37]
	s_nop 0
	v_addc_co_u32_e32 v25, vcc, 0, v151, vcc
	v_cvt_pk_bf16_f32 v31, v26, v27
	s_nop 0
	v_readfirstlane_b32 s82, v24
	v_readfirstlane_b32 s83, v25
	ds_write_b128 v230, v[28:31]
	ds_read_b128 v[236:239], v231
	s_nop 1
	s_waitcnt lgkmcnt(0)
	global_store_dwordx4 v233, v[236:239], s[82:83]
	v_cvt_pk_bf16_f32 v20, v20, v21
	v_cvt_pk_bf16_f32 v21, v22, v23
	v_cvt_pk_bf16_f32 v22, v16, v17
	v_cvt_pk_bf16_f32 v23, v18, v19
	s_nop 0
	v_readfirstlane_b32 s84, v32
	v_readfirstlane_b32 s85, v33
	ds_write_b128 v230, v[20:23]
	ds_read_b128 v[240:243], v231
	s_nop 1
	s_waitcnt lgkmcnt(0)
	global_store_dwordx4 v233, v[240:243], s[84:85] offset:256
	v_cvt_pk_bf16_f32 v12, v12, v13
	v_cvt_pk_bf16_f32 v13, v14, v15
	v_cvt_pk_bf16_f32 v14, v8, v9
	v_add_co_u32_e32 v8, vcc, 0x58000, v150
	v_lshl_add_u64 v[16:17], v[150:151], 0, s[38:39]
	s_nop 0
	v_addc_co_u32_e32 v9, vcc, 0, v151, vcc
	s_and_b64 vcc, exec, s[4:5]
	s_mov_b64 s[4:5], -1
	v_cvt_pk_bf16_f32 v15, v10, v11
	s_nop 0
	v_readfirstlane_b32 s82, v8
	v_readfirstlane_b32 s83, v9
	ds_write_b128 v230, v[12:15]
	ds_read_b128 v[236:239], v231
	s_nop 1
	s_waitcnt lgkmcnt(0)
	global_store_dwordx4 v233, v[236:239], s[82:83]
	v_cvt_pk_bf16_f32 v4, v4, v5
	v_cvt_pk_bf16_f32 v5, v6, v7
	v_cvt_pk_bf16_f32 v6, v0, v1
	v_cvt_pk_bf16_f32 v7, v2, v3
	s_nop 0
	v_readfirstlane_b32 s84, v16
	v_readfirstlane_b32 s85, v17
	ds_write_b128 v230, v[4:7]
	ds_read_b128 v[240:243], v231
	s_nop 1
	s_waitcnt lgkmcnt(0)
	global_store_dwordx4 v233, v[240:243], s[84:85] offset:256
	s_cbranch_vccnz .LBB0_293
	s_andn2_b64 vcc, exec, s[12:13]
	s_cbranch_vccnz .LBB0_292
	s_barrier
	s_branch .LBB0_292

.LBB0_473:
	s_or_b64 exec, exec, s[4:5]
	s_waitcnt lgkmcnt(0)
	s_barrier
	s_load_dwordx2 s[6:7], s[0:1], 0xb0
	v_mov_b32_e32 v8, v172
	v_and_b32_e32 v245, 63, v172
	v_lshrrev_b32_e32 v246, 6, v172
	v_mul_u32_u24_e32 v246, 0x7e0, v246
	v_add_u32_e32 v246, 0x20000, v246
	v_and_b32_e32 v247, 15, v245
	v_lshrrev_b32_e32 v234, 4, v245
	v_bfe_u32 v235, v247, 1, 2
	v_xor_b32_e32 v234, v234, v235
	v_lshlrev_b32_e32 v234, 4, v234
	v_lshl_add_u32 v234, v247, 6, v234
	v_add_u32_e32 v234, v234, v246
	v_lshrrev_b32_e32 v247, 2, v245
	v_and_b32_e32 v235, 3, v245
	v_bfe_u32 v244, v247, 1, 2
	v_xor_b32_e32 v235, v235, v244
	v_lshlrev_b32_e32 v235, 4, v235
	v_lshl_add_u32 v235, v247, 6, v235
	v_add_u32_e32 v235, v235, v246
	v_and_b32_e32 v244, 3, v245
	v_lshlrev_b32_e32 v244, 4, v244
	v_mul_u32_u24_e32 v247, 0x800, v247
	v_add_u32_e32 v244, v244, v247
	s_cmpk_lt_i32 s33, 0x200
	s_cselect_b64 s[8:9], -1, 0
	s_cmpk_gt_i32 s33, 0x1ff
	v_readfirstlane_b32 s22, v8
	s_cbranch_scc1 .LBB0_479
	s_ashr_i32 s2, s33, 31
	s_lshr_b32 s2, s2, 29
	s_add_i32 s2, s33, s2
	s_and_b32 s4, s2, -8
	s_sub_i32 s10, s33, s4
	s_cmp_gt_i32 s10, -1
	s_cbranch_scc0 .LBB0_476
	s_lshl_b32 s11, s10, 6
	s_cbranch_execz .LBB0_477
	s_branch .LBB0_478

.LBB0_495:
	v_lshl_or_b32 v168, s42, 8, v175
	v_lshl_add_u32 v188, s44, 8, v171
	v_ashrrev_i32_e32 v169, 31, v168
	v_ashrrev_i32_e32 v189, 31, v188
	v_lshlrev_b64 v[184:185], 1, v[168:169]
	v_lshl_add_u64 v[128:129], s[12:13], 0, v[184:185]
	v_lshlrev_b64 v[130:131], 11, v[188:189]
	v_lshl_add_u64 v[132:133], v[128:129], 0, v[130:131]
	global_load_dwordx4 v[210:213], v[132:133], off
	global_load_dwordx4 v[214:217], v[132:133], off offset:256
	v_lshl_add_u64 v[132:133], v[188:189], 2, s[18:19]
	global_load_dword v206, v[132:133], off
	v_or_b32_e32 v198, 16, v188
	v_or_b32_e32 v192, 32, v188
	v_or_b32_e32 v180, 48, v188
	v_ashrrev_i32_e32 v199, 31, v198
	v_ashrrev_i32_e32 v193, 31, v192
	v_ashrrev_i32_e32 v181, 31, v180
	v_lshl_add_u64 v[134:135], v[198:199], 2, s[18:19]
	v_lshlrev_b64 v[202:203], 11, v[198:199]
	v_lshlrev_b64 v[196:197], 11, v[192:193]
	v_lshlrev_b64 v[190:191], 11, v[180:181]
	v_add_u32_e32 v176, 0x80, v188
	v_lshl_add_u64 v[136:137], v[192:193], 2, s[18:19]
	v_lshl_add_u64 v[138:139], v[180:181], 2, s[18:19]
	v_lshl_add_u64 v[130:131], s[14:15], 0, v[130:131]
	global_load_dword v186, v[132:133], off offset:512
	global_load_dword v178, v[132:133], off offset:576
	global_load_dword v174, v[132:133], off offset:640
	global_load_dword v204, v[134:135], off
	global_load_dword v200, v[136:137], off
	global_load_dword v194, v[138:139], off
	global_load_dword v170, v[132:133], off offset:704
	v_lshl_add_u64 v[132:133], v[128:129], 0, v[202:203]
	v_lshl_add_u64 v[134:135], v[128:129], 0, v[196:197]
	v_lshl_add_u64 v[128:129], v[128:129], 0, v[190:191]
	v_ashrrev_i32_e32 v177, 31, v176
	v_lshl_add_u64 v[218:219], v[130:131], 0, v[184:185]
	global_load_dwordx4 v[148:151], v[132:133], off
	global_load_dwordx4 v[144:147], v[132:133], off offset:256
	global_load_dwordx4 v[140:143], v[134:135], off
	global_load_dwordx4 v[136:139], v[134:135], off offset:256
	s_nop 0
	global_load_dwordx4 v[132:135], v[128:129], off
	s_nop 0
	global_load_dwordx4 v[128:131], v[128:129], off offset:256
	v_lshlrev_b64 v[182:183], 11, v[176:177]
	v_lshl_add_u64 v[220:221], s[12:13], 0, v[182:183]
	v_lshl_add_u64 v[220:221], v[220:221], 0, v[184:185]
	s_waitcnt vmcnt(0)
	v_lshlrev_b32_e32 v222, 16, v210
	v_and_b32_e32 v223, 0xffff0000, v210
	v_lshlrev_b32_e32 v210, 16, v211
	v_and_b32_e32 v211, 0xffff0000, v211
	v_lshlrev_b32_e32 v224, 16, v212
	v_and_b32_e32 v225, 0xffff0000, v212
	v_lshlrev_b32_e32 v212, 16, v213
	v_and_b32_e32 v213, 0xffff0000, v213
	v_lshlrev_b32_e32 v226, 16, v214
	v_and_b32_e32 v227, 0xffff0000, v214
	v_lshlrev_b32_e32 v214, 16, v215
	v_and_b32_e32 v215, 0xffff0000, v215
	v_lshlrev_b32_e32 v228, 16, v216
	v_and_b32_e32 v229, 0xffff0000, v216
	v_lshlrev_b32_e32 v216, 16, v217
	v_and_b32_e32 v217, 0xffff0000, v217
	v_pk_fma_f32 v[210:211], v[126:127], v[206:207], v[210:211] op_sel_hi:[1,0,1]
	v_pk_fma_f32 v[222:223], v[124:125], v[206:207], v[222:223] op_sel_hi:[1,0,1]
	v_pk_fma_f32 v[122:123], v[122:123], v[206:207], v[212:213] op_sel_hi:[1,0,1]
	v_pk_fma_f32 v[120:121], v[120:121], v[206:207], v[224:225] op_sel_hi:[1,0,1]
	v_pk_fma_f32 v[212:213], v[118:119], v[206:207], v[214:215] op_sel_hi:[1,0,1]
	v_pk_fma_f32 v[214:215], v[116:117], v[206:207], v[226:227] op_sel_hi:[1,0,1]
	v_pk_fma_f32 v[216:217], v[114:115], v[206:207], v[216:217] op_sel_hi:[1,0,1]
	v_pk_fma_f32 v[206:207], v[112:113], v[206:207], v[228:229] op_sel_hi:[1,0,1]
	v_cvt_pk_bf16_f32 v112, v222, v223
	v_cvt_pk_bf16_f32 v113, v210, v211
	v_cvt_pk_bf16_f32 v114, v120, v121
	v_cvt_pk_bf16_f32 v115, v122, v123
	s_nop 0
	v_readfirstlane_b32 s82, v218
	v_readfirstlane_b32 s83, v219
	ds_write_b128 v234, v[112:115]
	ds_read_b128 v[236:239], v235
	s_nop 1
	s_waitcnt lgkmcnt(0)
	global_store_dwordx4 v244, v[236:239], s[82:83]
	v_cvt_pk_bf16_f32 v124, v214, v215
	v_cvt_pk_bf16_f32 v125, v212, v213
	v_cvt_pk_bf16_f32 v126, v206, v207
	v_cvt_pk_bf16_f32 v127, v216, v217
	global_load_dwordx4 v[116:119], v[220:221], off
	global_load_dwordx4 v[112:115], v[220:221], off offset:256
	v_mul_f32_e32 v121, v121, v121
	v_fmac_f32_e32 v121, v120, v120
	v_mul_f32_e32 v120, v123, v123
	v_fmac_f32_e32 v120, v122, v122
	v_add_f32_e32 v120, v121, v120
	v_mul_f32_e32 v121, v215, v215
	v_mul_f32_e32 v122, v213, v213
	v_fmac_f32_e32 v121, v214, v214
	v_fmac_f32_e32 v122, v212, v212
	v_mul_f32_e32 v205, v223, v223
	v_mul_f32_e32 v209, v211, v211
	v_add_f32_e32 v121, v121, v122
	v_mul_f32_e32 v122, v207, v207
	v_mul_f32_e32 v123, v217, v217
	v_fmac_f32_e32 v205, v222, v222
	v_fmac_f32_e32 v209, v210, v210
	v_fmac_f32_e32 v122, v206, v206
	v_fmac_f32_e32 v123, v216, v216
	v_add_f32_e32 v205, v205, v209
	v_add_f32_e32 v122, v122, v123
	v_add_f32_e32 v120, v205, v120
	v_add_f32_e32 v121, v121, v122
	v_and_b32_e32 v122, 64, v201
	v_add_f32_e32 v120, v120, v121
	v_xor_b32_e32 v121, 16, v201
	v_add_u32_e32 v123, 64, v122
	v_cmp_lt_i32_e32 vcc, v121, v123
	s_nop 0
	v_readfirstlane_b32 s84, v218
	v_readfirstlane_b32 s85, v219
	ds_write_b128 v234, v[124:127]
	ds_read_b128 v[240:243], v235
	s_nop 1
	s_waitcnt lgkmcnt(0)
	global_store_dwordx4 v244, v[240:243], s[84:85] offset:256
	s_nop 0
	v_cndmask_b32_e32 v121, v201, v121, vcc
	v_lshlrev_b32_e32 v122, 2, v121
	ds_bpermute_b32 v121, v122, v120
	s_waitcnt lgkmcnt(0)
	v_add_f32_e32 v120, v120, v121
	v_xor_b32_e32 v121, 32, v201
	v_cmp_lt_i32_e32 vcc, v121, v123
	s_nop 1
	v_cndmask_b32_e32 v121, v201, v121, vcc
	v_lshlrev_b32_e32 v123, 2, v121
	ds_bpermute_b32 v121, v123, v120
	s_and_saveexec_b64 s[42:43], s[6:7]
	s_cbranch_execz .LBB0_497
	v_lshl_add_u64 v[124:125], v[188:189], 2, s[16:17]
	s_waitcnt lgkmcnt(0)
	v_add_f32_e32 v120, v120, v121
	global_atomic_add_f32 v[124:125], v120, off
.LBB0_497:
	s_or_b64 exec, exec, s[42:43]
	v_lshlrev_b32_e32 v124, 16, v148
	v_and_b32_e32 v125, 0xffff0000, v148
	v_lshlrev_b32_e32 v126, 16, v149
	v_and_b32_e32 v127, 0xffff0000, v149
	v_lshlrev_b32_e32 v148, 16, v150
	v_and_b32_e32 v149, 0xffff0000, v150
	v_lshlrev_b32_e32 v150, 16, v151
	v_and_b32_e32 v151, 0xffff0000, v151
	v_pk_fma_f32 v[124:125], v[108:109], v[204:205], v[124:125] op_sel_hi:[1,0,1]
	v_lshl_add_u64 v[108:109], s[14:15], 0, v[202:203]
	v_add_u32_e32 v120, 0x90, v188
	v_pk_fma_f32 v[126:127], v[110:111], v[204:205], v[126:127] op_sel_hi:[1,0,1]
	v_pk_fma_f32 v[150:151], v[106:107], v[204:205], v[150:151] op_sel_hi:[1,0,1]
	v_pk_fma_f32 v[148:149], v[104:105], v[204:205], v[148:149] op_sel_hi:[1,0,1]
	v_cvt_pk_bf16_f32 v104, v124, v125
	v_cvt_pk_bf16_f32 v105, v126, v127
	v_lshl_add_u64 v[202:203], v[108:109], 0, v[184:185]
	v_cvt_pk_bf16_f32 v106, v148, v149
	v_cvt_pk_bf16_f32 v107, v150, v151
	s_waitcnt lgkmcnt(0)
	v_ashrrev_i32_e32 v121, 31, v120
	s_nop 0
	v_readfirstlane_b32 s82, v202
	v_readfirstlane_b32 s83, v203
	ds_write_b128 v234, v[104:107]
	ds_read_b128 v[236:239], v235
	s_nop 1
	s_waitcnt lgkmcnt(0)
	global_store_dwordx4 v244, v[236:239], s[82:83]
	v_lshlrev_b32_e32 v108, 16, v146
	v_and_b32_e32 v109, 0xffff0000, v146
	v_lshlrev_b32_e32 v106, 16, v145
	v_and_b32_e32 v107, 0xffff0000, v145
	v_lshlrev_b32_e32 v104, 16, v144
	v_and_b32_e32 v105, 0xffff0000, v144
	v_lshlrev_b32_e32 v110, 16, v147
	v_and_b32_e32 v111, 0xffff0000, v147
	v_pk_fma_f32 v[144:145], v[102:103], v[204:205], v[106:107] op_sel_hi:[1,0,1]
	v_lshlrev_b64 v[106:107], 11, v[120:121]
	v_pk_fma_f32 v[104:105], v[100:101], v[204:205], v[104:105] op_sel_hi:[1,0,1]
	v_pk_fma_f32 v[146:147], v[98:99], v[204:205], v[110:111] op_sel_hi:[1,0,1]
	v_pk_fma_f32 v[204:205], v[96:97], v[204:205], v[108:109] op_sel_hi:[1,0,1]
	v_lshl_add_u64 v[96:97], s[12:13], 0, v[106:107]
	v_lshl_add_u64 v[96:97], v[96:97], 0, v[184:185]
	v_cvt_pk_bf16_f32 v108, v104, v105
	v_cvt_pk_bf16_f32 v109, v144, v145
	v_cvt_pk_bf16_f32 v110, v204, v205
	v_cvt_pk_bf16_f32 v111, v146, v147
	global_load_dwordx4 v[100:103], v[96:97], off
	s_nop 0
	global_load_dwordx4 v[96:99], v[96:97], off offset:256
	v_mul_f32_e32 v125, v125, v125
	v_fmac_f32_e32 v125, v124, v124
	v_mul_f32_e32 v124, v127, v127
	v_fmac_f32_e32 v124, v126, v126
	v_add_f32_e32 v124, v125, v124
	v_mul_f32_e32 v125, v149, v149
	v_mul_f32_e32 v126, v151, v151
	v_mul_f32_e32 v105, v105, v105
	v_fmac_f32_e32 v125, v148, v148
	v_fmac_f32_e32 v126, v150, v150
	v_fmac_f32_e32 v105, v104, v104
	v_mul_f32_e32 v104, v145, v145
	v_add_f32_e32 v125, v125, v126
	v_fmac_f32_e32 v104, v144, v144
	v_add_f32_e32 v124, v124, v125
	v_add_f32_e32 v104, v105, v104
	v_mul_f32_e32 v105, v205, v205
	v_mul_f32_e32 v125, v147, v147
	v_fmac_f32_e32 v105, v204, v204
	v_fmac_f32_e32 v125, v146, v146
	v_add_f32_e32 v105, v105, v125
	v_add_f32_e32 v104, v104, v105
	v_add_f32_e32 v104, v124, v104
	ds_bpermute_b32 v105, v122, v104
	s_nop 0
	v_readfirstlane_b32 s84, v202
	v_readfirstlane_b32 s85, v203
	ds_write_b128 v234, v[108:111]
	ds_read_b128 v[240:243], v235
	s_nop 1
	s_waitcnt lgkmcnt(0)
	global_store_dwordx4 v244, v[240:243], s[84:85] offset:256
	s_waitcnt lgkmcnt(0)
	v_add_f32_e32 v104, v104, v105
	ds_bpermute_b32 v105, v123, v104
	s_and_saveexec_b64 s[42:43], s[6:7]
	s_cbranch_execz .LBB0_499
	v_lshl_add_u64 v[108:109], v[198:199], 2, s[16:17]
	s_waitcnt lgkmcnt(0)
	v_add_f32_e32 v104, v104, v105
	global_atomic_add_f32 v[108:109], v104, off
.LBB0_499:
	s_or_b64 exec, exec, s[42:43]
	v_lshlrev_b32_e32 v108, 16, v140
	v_and_b32_e32 v109, 0xffff0000, v140
	v_lshlrev_b32_e32 v110, 16, v141
	v_and_b32_e32 v111, 0xffff0000, v141
	v_lshlrev_b32_e32 v124, 16, v142
	v_and_b32_e32 v125, 0xffff0000, v142
	v_lshlrev_b32_e32 v126, 16, v143
	v_and_b32_e32 v127, 0xffff0000, v143
	v_pk_fma_f32 v[108:109], v[92:93], v[200:201], v[108:109] op_sel_hi:[1,0,1]
	v_lshl_add_u64 v[92:93], s[14:15], 0, v[196:197]
	v_add_u32_e32 v104, 0xa0, v188
	v_pk_fma_f32 v[110:111], v[94:95], v[200:201], v[110:111] op_sel_hi:[1,0,1]
	v_pk_fma_f32 v[126:127], v[90:91], v[200:201], v[126:127] op_sel_hi:[1,0,1]
	v_pk_fma_f32 v[124:125], v[88:89], v[200:201], v[124:125] op_sel_hi:[1,0,1]
	v_cvt_pk_bf16_f32 v88, v108, v109
	v_cvt_pk_bf16_f32 v89, v110, v111
	v_lshl_add_u64 v[140:141], v[92:93], 0, v[184:185]
	v_cvt_pk_bf16_f32 v90, v124, v125
	v_cvt_pk_bf16_f32 v91, v126, v127
	s_waitcnt lgkmcnt(0)
	v_ashrrev_i32_e32 v105, 31, v104
	s_nop 0
	v_readfirstlane_b32 s82, v140
	v_readfirstlane_b32 s83, v141
	ds_write_b128 v234, v[88:91]
	ds_read_b128 v[236:239], v235
	s_nop 1
	s_waitcnt lgkmcnt(0)
	global_store_dwordx4 v244, v[236:239], s[82:83]
	v_lshlrev_b32_e32 v92, 16, v138
	v_and_b32_e32 v93, 0xffff0000, v138
	v_lshlrev_b32_e32 v90, 16, v137
	v_and_b32_e32 v91, 0xffff0000, v137
	v_lshlrev_b32_e32 v88, 16, v136
	v_and_b32_e32 v89, 0xffff0000, v136
	v_pk_fma_f32 v[136:137], v[86:87], v[200:201], v[90:91] op_sel_hi:[1,0,1]
	v_lshlrev_b64 v[90:91], 11, v[104:105]
	v_pk_fma_f32 v[142:143], v[80:81], v[200:201], v[92:93] op_sel_hi:[1,0,1]
	v_lshl_add_u64 v[80:81], s[12:13], 0, v[90:91]
	v_lshlrev_b32_e32 v94, 16, v139
	v_and_b32_e32 v95, 0xffff0000, v139
	v_lshl_add_u64 v[80:81], v[80:81], 0, v[184:185]
	v_pk_fma_f32 v[88:89], v[84:85], v[200:201], v[88:89] op_sel_hi:[1,0,1]
	v_pk_fma_f32 v[138:139], v[82:83], v[200:201], v[94:95] op_sel_hi:[1,0,1]
	v_cvt_pk_bf16_f32 v92, v88, v89
	v_cvt_pk_bf16_f32 v93, v136, v137
	v_cvt_pk_bf16_f32 v94, v142, v143
	v_mul_f32_e32 v109, v109, v109
	v_cvt_pk_bf16_f32 v95, v138, v139
	global_load_dwordx4 v[84:87], v[80:81], off
	s_nop 0
	global_load_dwordx4 v[80:83], v[80:81], off offset:256
	v_fmac_f32_e32 v109, v108, v108
	v_mul_f32_e32 v108, v111, v111
	v_fmac_f32_e32 v108, v110, v110
	v_add_f32_e32 v108, v109, v108
	v_mul_f32_e32 v109, v125, v125
	v_mul_f32_e32 v110, v127, v127
	v_mul_f32_e32 v89, v89, v89
	v_fmac_f32_e32 v109, v124, v124
	v_fmac_f32_e32 v110, v126, v126
	v_fmac_f32_e32 v89, v88, v88
	v_mul_f32_e32 v88, v137, v137
	v_add_f32_e32 v109, v109, v110
	v_fmac_f32_e32 v88, v136, v136
	v_add_f32_e32 v108, v108, v109
	v_add_f32_e32 v88, v89, v88
	v_mul_f32_e32 v89, v143, v143
	v_mul_f32_e32 v109, v139, v139
	v_fmac_f32_e32 v89, v142, v142
	v_fmac_f32_e32 v109, v138, v138
	v_add_f32_e32 v89, v89, v109
	v_add_f32_e32 v88, v88, v89
	v_add_f32_e32 v88, v108, v88
	ds_bpermute_b32 v89, v122, v88
	s_nop 0
	v_readfirstlane_b32 s84, v140
	v_readfirstlane_b32 s85, v141
	ds_write_b128 v234, v[92:95]
	ds_read_b128 v[240:243], v235
	s_nop 1
	s_waitcnt lgkmcnt(0)
	global_store_dwordx4 v244, v[240:243], s[84:85] offset:256
	s_waitcnt lgkmcnt(0)
	v_add_f32_e32 v88, v88, v89
	ds_bpermute_b32 v89, v123, v88
	s_and_saveexec_b64 s[42:43], s[6:7]
	s_cbranch_execz .LBB0_501
	v_lshl_add_u64 v[92:93], v[192:193], 2, s[16:17]
	s_waitcnt lgkmcnt(0)
	v_add_f32_e32 v88, v88, v89
	global_atomic_add_f32 v[92:93], v88, off
.LBB0_501:
	s_or_b64 exec, exec, s[42:43]
	v_lshlrev_b32_e32 v92, 16, v132
	v_and_b32_e32 v93, 0xffff0000, v132
	v_lshlrev_b32_e32 v94, 16, v133
	v_and_b32_e32 v95, 0xffff0000, v133
	v_lshlrev_b32_e32 v108, 16, v134
	v_and_b32_e32 v109, 0xffff0000, v134
	v_pk_fma_f32 v[92:93], v[76:77], v[194:195], v[92:93] op_sel_hi:[1,0,1]
	v_lshl_add_u64 v[76:77], s[14:15], 0, v[190:191]
	v_add_u32_e32 v88, 0xb0, v188
	v_lshlrev_b32_e32 v110, 16, v135
	v_and_b32_e32 v111, 0xffff0000, v135
	v_pk_fma_f32 v[94:95], v[78:79], v[194:195], v[94:95] op_sel_hi:[1,0,1]
	v_pk_fma_f32 v[108:109], v[72:73], v[194:195], v[108:109] op_sel_hi:[1,0,1]
	v_cvt_pk_bf16_f32 v72, v92, v93
	v_cvt_pk_bf16_f32 v73, v94, v95
	v_lshl_add_u64 v[124:125], v[76:77], 0, v[184:185]
	s_waitcnt lgkmcnt(0)
	v_ashrrev_i32_e32 v89, 31, v88
	v_pk_fma_f32 v[110:111], v[74:75], v[194:195], v[110:111] op_sel_hi:[1,0,1]
	v_cvt_pk_bf16_f32 v74, v108, v109
	v_lshlrev_b32_e32 v76, 16, v130
	v_cvt_pk_bf16_f32 v75, v110, v111
	s_nop 0
	v_readfirstlane_b32 s82, v124
	v_readfirstlane_b32 s83, v125
	ds_write_b128 v234, v[72:75]
	ds_read_b128 v[236:239], v235
	s_nop 1
	s_waitcnt lgkmcnt(0)
	global_store_dwordx4 v244, v[236:239], s[82:83]
	v_and_b32_e32 v77, 0xffff0000, v130
	v_lshlrev_b32_e32 v78, 16, v131
	v_lshlrev_b32_e32 v72, 16, v128
	v_and_b32_e32 v73, 0xffff0000, v128
	v_pk_fma_f32 v[126:127], v[68:69], v[194:195], v[72:73] op_sel_hi:[1,0,1]
	v_lshlrev_b64 v[72:73], 11, v[88:89]
	v_and_b32_e32 v79, 0xffff0000, v131
	v_pk_fma_f32 v[130:131], v[64:65], v[194:195], v[76:77] op_sel_hi:[1,0,1]
	v_lshl_add_u64 v[64:65], s[12:13], 0, v[72:73]
	v_lshlrev_b32_e32 v74, 16, v129
	v_and_b32_e32 v75, 0xffff0000, v129
	v_lshl_add_u64 v[64:65], v[64:65], 0, v[184:185]
	v_pk_fma_f32 v[74:75], v[70:71], v[194:195], v[74:75] op_sel_hi:[1,0,1]
	v_pk_fma_f32 v[128:129], v[66:67], v[194:195], v[78:79] op_sel_hi:[1,0,1]
	v_cvt_pk_bf16_f32 v76, v126, v127
	v_cvt_pk_bf16_f32 v77, v74, v75
	v_cvt_pk_bf16_f32 v78, v130, v131
	v_mul_f32_e32 v93, v93, v93
	v_cvt_pk_bf16_f32 v79, v128, v129
	global_load_dwordx4 v[68:71], v[64:65], off
	s_nop 0
	global_load_dwordx4 v[64:67], v[64:65], off offset:256
	v_fmac_f32_e32 v93, v92, v92
	v_mul_f32_e32 v92, v95, v95
	v_fmac_f32_e32 v92, v94, v94
	v_add_f32_e32 v92, v93, v92
	v_mul_f32_e32 v93, v109, v109
	v_mul_f32_e32 v94, v111, v111
	v_fmac_f32_e32 v93, v108, v108
	v_fmac_f32_e32 v94, v110, v110
	v_add_f32_e32 v93, v93, v94
	v_add_f32_e32 v92, v92, v93
	v_mul_f32_e32 v93, v127, v127
	v_mul_f32_e32 v75, v75, v75
	v_fmac_f32_e32 v93, v126, v126
	v_fmac_f32_e32 v75, v74, v74
	v_add_f32_e32 v74, v93, v75
	v_mul_f32_e32 v75, v131, v131
	v_mul_f32_e32 v93, v129, v129
	v_fmac_f32_e32 v75, v130, v130
	v_fmac_f32_e32 v93, v128, v128
	v_add_f32_e32 v75, v75, v93
	v_add_f32_e32 v74, v74, v75
	v_add_f32_e32 v74, v92, v74
	ds_bpermute_b32 v75, v122, v74
	s_nop 0
	v_readfirstlane_b32 s84, v124
	v_readfirstlane_b32 s85, v125
	ds_write_b128 v234, v[76:79]
	ds_read_b128 v[240:243], v235
	s_nop 1
	s_waitcnt lgkmcnt(0)
	global_store_dwordx4 v244, v[240:243], s[84:85] offset:256
	s_waitcnt lgkmcnt(0)
	v_add_f32_e32 v74, v74, v75
	ds_bpermute_b32 v75, v123, v74
	s_and_saveexec_b64 s[42:43], s[6:7]
	s_cbranch_execz .LBB0_503
	v_lshl_add_u64 v[76:77], v[180:181], 2, s[16:17]
	s_waitcnt lgkmcnt(0)
	v_add_f32_e32 v74, v74, v75
	global_atomic_add_f32 v[76:77], v74, off
.LBB0_503:
	s_or_b64 exec, exec, s[42:43]
	s_waitcnt vmcnt(14)
	v_lshlrev_b32_e32 v74, 16, v116
	s_waitcnt lgkmcnt(0)
	v_and_b32_e32 v75, 0xffff0000, v116
	v_lshlrev_b32_e32 v76, 16, v117
	v_and_b32_e32 v77, 0xffff0000, v117
	v_lshlrev_b32_e32 v92, 16, v119
	v_and_b32_e32 v93, 0xffff0000, v119
	v_pk_fma_f32 v[62:63], v[62:63], v[186:187], v[76:77] op_sel_hi:[1,0,1]
	v_pk_fma_f32 v[60:61], v[60:61], v[186:187], v[74:75] op_sel_hi:[1,0,1]
	v_pk_fma_f32 v[74:75], v[58:59], v[186:187], v[92:93] op_sel_hi:[1,0,1]
	s_waitcnt vmcnt(13)
	v_lshlrev_b32_e32 v92, 16, v113
	v_and_b32_e32 v93, 0xffff0000, v113
	v_lshlrev_b32_e32 v94, 16, v114
	v_and_b32_e32 v95, 0xffff0000, v114
	v_lshlrev_b32_e32 v78, 16, v118
	v_and_b32_e32 v79, 0xffff0000, v118
	v_pk_fma_f32 v[54:55], v[54:55], v[186:187], v[92:93] op_sel_hi:[1,0,1]
	v_pk_fma_f32 v[92:93], v[48:49], v[186:187], v[94:95] op_sel_hi:[1,0,1]
	v_mul_f32_e32 v48, v61, v61
	v_mul_f32_e32 v49, v63, v63
	v_pk_fma_f32 v[76:77], v[56:57], v[186:187], v[78:79] op_sel_hi:[1,0,1]
	v_lshlrev_b32_e32 v78, 16, v112
	v_and_b32_e32 v79, 0xffff0000, v112
	v_lshlrev_b32_e32 v108, 16, v115
	v_and_b32_e32 v109, 0xffff0000, v115
	v_fmac_f32_e32 v48, v60, v60
	v_fmac_f32_e32 v49, v62, v62
	v_pk_fma_f32 v[52:53], v[52:53], v[186:187], v[78:79] op_sel_hi:[1,0,1]
	v_pk_fma_f32 v[78:79], v[50:51], v[186:187], v[108:109] op_sel_hi:[1,0,1]
	v_add_f32_e32 v48, v48, v49
	v_mul_f32_e32 v49, v77, v77
	v_mul_f32_e32 v50, v75, v75
	v_fmac_f32_e32 v49, v76, v76
	v_fmac_f32_e32 v50, v74, v74
	v_add_f32_e32 v49, v49, v50
	v_add_f32_e32 v48, v48, v49
	v_mul_f32_e32 v49, v53, v53
	v_mul_f32_e32 v50, v55, v55
	v_fmac_f32_e32 v49, v52, v52
	v_fmac_f32_e32 v50, v54, v54
	v_add_f32_e32 v49, v49, v50
	v_mul_f32_e32 v50, v93, v93
	v_mul_f32_e32 v51, v79, v79
	v_fmac_f32_e32 v50, v92, v92
	v_fmac_f32_e32 v51, v78, v78
	v_add_f32_e32 v50, v50, v51
	v_add_f32_e32 v49, v49, v50
	v_add_f32_e32 v51, v48, v49
	v_cvt_pk_bf16_f32 v56, v60, v61
	v_cvt_pk_bf16_f32 v57, v62, v63
	ds_bpermute_b32 v62, v122, v51
	v_lshl_add_u64 v[48:49], s[14:15], 0, v[182:183]
	v_lshl_add_u64 v[60:61], v[168:169], 1, v[48:49]
	v_cvt_pk_bf16_f32 v58, v76, v77
	v_cvt_pk_bf16_f32 v59, v74, v75
	s_waitcnt lgkmcnt(0)
	v_add_f32_e32 v48, v51, v62
	ds_bpermute_b32 v49, v123, v48
	s_nop 0
	v_readfirstlane_b32 s82, v60
	v_readfirstlane_b32 s83, v61
	ds_write_b128 v234, v[56:59]
	ds_read_b128 v[236:239], v235
	s_nop 1
	s_waitcnt lgkmcnt(0)
	global_store_dwordx4 v244, v[236:239], s[82:83]
	v_cvt_pk_bf16_f32 v50, v52, v53
	v_cvt_pk_bf16_f32 v51, v54, v55
	v_cvt_pk_bf16_f32 v52, v92, v93
	v_cvt_pk_bf16_f32 v53, v78, v79
	s_nop 0
	v_readfirstlane_b32 s84, v60
	v_readfirstlane_b32 s85, v61
	ds_write_b128 v234, v[50:53]
	ds_read_b128 v[240:243], v235
	s_nop 1
	s_waitcnt lgkmcnt(0)
	global_store_dwordx4 v244, v[240:243], s[84:85] offset:256
	s_and_saveexec_b64 s[42:43], s[6:7]
	s_cbranch_execz .LBB0_505
	v_lshl_add_u64 v[50:51], v[176:177], 2, s[16:17]
	s_waitcnt lgkmcnt(0)
	v_add_f32_e32 v48, v48, v49
	global_atomic_add_f32 v[50:51], v48, off
.LBB0_505:
	s_or_b64 exec, exec, s[42:43]
	s_waitcnt vmcnt(12)
	v_lshlrev_b32_e32 v48, 16, v100
	s_waitcnt lgkmcnt(0)
	v_and_b32_e32 v49, 0xffff0000, v100
	v_lshlrev_b32_e32 v50, 16, v101
	v_and_b32_e32 v51, 0xffff0000, v101
	v_lshlrev_b32_e32 v54, 16, v103
	v_and_b32_e32 v55, 0xffff0000, v103
	v_pk_fma_f32 v[46:47], v[46:47], v[178:179], v[50:51] op_sel_hi:[1,0,1]
	v_pk_fma_f32 v[44:45], v[44:45], v[178:179], v[48:49] op_sel_hi:[1,0,1]
	v_pk_fma_f32 v[48:49], v[42:43], v[178:179], v[54:55] op_sel_hi:[1,0,1]
	s_waitcnt vmcnt(11)
	v_lshlrev_b32_e32 v54, 16, v97
	v_and_b32_e32 v55, 0xffff0000, v97
	v_lshlrev_b32_e32 v56, 16, v98
	v_and_b32_e32 v57, 0xffff0000, v98
	v_lshlrev_b32_e32 v52, 16, v102
	v_and_b32_e32 v53, 0xffff0000, v102
	v_pk_fma_f32 v[38:39], v[38:39], v[178:179], v[54:55] op_sel_hi:[1,0,1]
	v_pk_fma_f32 v[54:55], v[32:33], v[178:179], v[56:57] op_sel_hi:[1,0,1]
	v_mul_f32_e32 v32, v45, v45
	v_mul_f32_e32 v33, v47, v47
	v_pk_fma_f32 v[50:51], v[40:41], v[178:179], v[52:53] op_sel_hi:[1,0,1]
	v_lshlrev_b32_e32 v52, 16, v96
	v_and_b32_e32 v53, 0xffff0000, v96
	v_lshlrev_b32_e32 v58, 16, v99
	v_and_b32_e32 v59, 0xffff0000, v99
	v_fmac_f32_e32 v32, v44, v44
	v_fmac_f32_e32 v33, v46, v46
	v_pk_fma_f32 v[36:37], v[36:37], v[178:179], v[52:53] op_sel_hi:[1,0,1]
	v_pk_fma_f32 v[52:53], v[34:35], v[178:179], v[58:59] op_sel_hi:[1,0,1]
	v_add_f32_e32 v32, v32, v33
	v_mul_f32_e32 v33, v51, v51
	v_mul_f32_e32 v34, v49, v49
	v_fmac_f32_e32 v33, v50, v50
	v_fmac_f32_e32 v34, v48, v48
	v_add_f32_e32 v33, v33, v34
	v_add_f32_e32 v32, v32, v33
	v_mul_f32_e32 v33, v37, v37
	v_mul_f32_e32 v34, v39, v39
	v_fmac_f32_e32 v33, v36, v36
	v_fmac_f32_e32 v34, v38, v38
	v_add_f32_e32 v33, v33, v34
	v_mul_f32_e32 v34, v55, v55
	v_mul_f32_e32 v35, v53, v53
	v_fmac_f32_e32 v34, v54, v54
	v_fmac_f32_e32 v35, v52, v52
	v_add_f32_e32 v34, v34, v35
	v_add_f32_e32 v33, v33, v34
	v_add_f32_e32 v35, v32, v33
	v_cvt_pk_bf16_f32 v40, v44, v45
	v_cvt_pk_bf16_f32 v41, v46, v47
	ds_bpermute_b32 v46, v122, v35
	v_lshl_add_u64 v[32:33], s[14:15], 0, v[106:107]
	v_lshl_add_u64 v[44:45], v[168:169], 1, v[32:33]
	v_cvt_pk_bf16_f32 v42, v50, v51
	v_cvt_pk_bf16_f32 v43, v48, v49
	s_waitcnt lgkmcnt(0)
	v_add_f32_e32 v32, v35, v46
	ds_bpermute_b32 v33, v123, v32
	s_nop 0
	v_readfirstlane_b32 s82, v44
	v_readfirstlane_b32 s83, v45
	ds_write_b128 v234, v[40:43]
	ds_read_b128 v[236:239], v235
	s_nop 1
	s_waitcnt lgkmcnt(0)
	global_store_dwordx4 v244, v[236:239], s[82:83]
	v_cvt_pk_bf16_f32 v34, v36, v37
	v_cvt_pk_bf16_f32 v35, v38, v39
	v_cvt_pk_bf16_f32 v36, v54, v55
	v_cvt_pk_bf16_f32 v37, v52, v53
	s_nop 0
	v_readfirstlane_b32 s84, v44
	v_readfirstlane_b32 s85, v45
	ds_write_b128 v234, v[34:37]
	ds_read_b128 v[240:243], v235
	s_nop 1
	s_waitcnt lgkmcnt(0)
	global_store_dwordx4 v244, v[240:243], s[84:85] offset:256
	s_and_saveexec_b64 s[42:43], s[6:7]
	s_cbranch_execz .LBB0_507
	v_lshl_add_u64 v[34:35], v[120:121], 2, s[16:17]
	s_waitcnt lgkmcnt(0)
	v_add_f32_e32 v32, v32, v33
	global_atomic_add_f32 v[34:35], v32, off
.LBB0_507:
	s_or_b64 exec, exec, s[42:43]
	s_waitcnt vmcnt(10)
	v_lshlrev_b32_e32 v32, 16, v84
	s_waitcnt lgkmcnt(0)
	v_and_b32_e32 v33, 0xffff0000, v84
	v_lshlrev_b32_e32 v34, 16, v85
	v_and_b32_e32 v35, 0xffff0000, v85
	v_lshlrev_b32_e32 v38, 16, v87
	v_and_b32_e32 v39, 0xffff0000, v87
	v_pk_fma_f32 v[30:31], v[30:31], v[174:175], v[34:35] op_sel_hi:[1,0,1]
	v_pk_fma_f32 v[28:29], v[28:29], v[174:175], v[32:33] op_sel_hi:[1,0,1]
	v_pk_fma_f32 v[32:33], v[26:27], v[174:175], v[38:39] op_sel_hi:[1,0,1]
	s_waitcnt vmcnt(9)
	v_lshlrev_b32_e32 v38, 16, v81
	v_and_b32_e32 v39, 0xffff0000, v81
	v_lshlrev_b32_e32 v40, 16, v82
	v_and_b32_e32 v41, 0xffff0000, v82
	v_lshlrev_b32_e32 v36, 16, v86
	v_and_b32_e32 v37, 0xffff0000, v86
	v_pk_fma_f32 v[22:23], v[22:23], v[174:175], v[38:39] op_sel_hi:[1,0,1]
	v_pk_fma_f32 v[38:39], v[16:17], v[174:175], v[40:41] op_sel_hi:[1,0,1]
	v_mul_f32_e32 v16, v29, v29
	v_mul_f32_e32 v17, v31, v31
	v_pk_fma_f32 v[34:35], v[24:25], v[174:175], v[36:37] op_sel_hi:[1,0,1]
	v_lshlrev_b32_e32 v36, 16, v80
	v_and_b32_e32 v37, 0xffff0000, v80
	v_lshlrev_b32_e32 v42, 16, v83
	v_and_b32_e32 v43, 0xffff0000, v83
	v_fmac_f32_e32 v16, v28, v28
	v_fmac_f32_e32 v17, v30, v30
	v_pk_fma_f32 v[20:21], v[20:21], v[174:175], v[36:37] op_sel_hi:[1,0,1]
	v_pk_fma_f32 v[36:37], v[18:19], v[174:175], v[42:43] op_sel_hi:[1,0,1]
	v_add_f32_e32 v16, v16, v17
	v_mul_f32_e32 v17, v35, v35
	v_mul_f32_e32 v18, v33, v33
	v_fmac_f32_e32 v17, v34, v34
	v_fmac_f32_e32 v18, v32, v32
	v_add_f32_e32 v17, v17, v18
	v_add_f32_e32 v16, v16, v17
	v_mul_f32_e32 v17, v21, v21
	v_mul_f32_e32 v18, v23, v23
	v_fmac_f32_e32 v17, v20, v20
	v_fmac_f32_e32 v18, v22, v22
	v_add_f32_e32 v17, v17, v18
	v_mul_f32_e32 v18, v39, v39
	v_mul_f32_e32 v19, v37, v37
	v_fmac_f32_e32 v18, v38, v38
	v_fmac_f32_e32 v19, v36, v36
	v_add_f32_e32 v18, v18, v19
	v_add_f32_e32 v17, v17, v18
	v_add_f32_e32 v19, v16, v17
	v_cvt_pk_bf16_f32 v24, v28, v29
	v_cvt_pk_bf16_f32 v25, v30, v31
	ds_bpermute_b32 v30, v122, v19
	v_lshl_add_u64 v[16:17], s[14:15], 0, v[90:91]
	v_lshl_add_u64 v[28:29], v[168:169], 1, v[16:17]
	v_cvt_pk_bf16_f32 v26, v34, v35
	v_cvt_pk_bf16_f32 v27, v32, v33
	s_waitcnt lgkmcnt(0)
	v_add_f32_e32 v16, v19, v30
	ds_bpermute_b32 v17, v123, v16
	s_nop 0
	v_readfirstlane_b32 s82, v28
	v_readfirstlane_b32 s83, v29
	ds_write_b128 v234, v[24:27]
	ds_read_b128 v[236:239], v235
	s_nop 1
	s_waitcnt lgkmcnt(0)
	global_store_dwordx4 v244, v[236:239], s[82:83]
	v_cvt_pk_bf16_f32 v18, v20, v21
	v_cvt_pk_bf16_f32 v19, v22, v23
	v_cvt_pk_bf16_f32 v20, v38, v39
	v_cvt_pk_bf16_f32 v21, v36, v37
	s_nop 0
	v_readfirstlane_b32 s84, v28
	v_readfirstlane_b32 s85, v29
	ds_write_b128 v234, v[18:21]
	ds_read_b128 v[240:243], v235
	s_nop 1
	s_waitcnt lgkmcnt(0)
	global_store_dwordx4 v244, v[240:243], s[84:85] offset:256
	s_and_saveexec_b64 s[42:43], s[6:7]
	s_cbranch_execz .LBB0_509
	v_lshl_add_u64 v[18:19], v[104:105], 2, s[16:17]
	s_waitcnt lgkmcnt(0)
	v_add_f32_e32 v16, v16, v17
	global_atomic_add_f32 v[18:19], v16, off
.LBB0_509:
	s_or_b64 exec, exec, s[42:43]
	s_waitcnt vmcnt(8)
	v_lshlrev_b32_e32 v16, 16, v68
	s_waitcnt lgkmcnt(0)
	v_and_b32_e32 v17, 0xffff0000, v68
	v_lshlrev_b32_e32 v18, 16, v69
	v_and_b32_e32 v19, 0xffff0000, v69
	v_lshlrev_b32_e32 v22, 16, v71
	v_and_b32_e32 v23, 0xffff0000, v71
	v_pk_fma_f32 v[14:15], v[14:15], v[170:171], v[18:19] op_sel_hi:[1,0,1]
	v_pk_fma_f32 v[12:13], v[12:13], v[170:171], v[16:17] op_sel_hi:[1,0,1]
	v_pk_fma_f32 v[16:17], v[10:11], v[170:171], v[22:23] op_sel_hi:[1,0,1]
	s_waitcnt vmcnt(7)
	v_lshlrev_b32_e32 v22, 16, v65
	v_and_b32_e32 v23, 0xffff0000, v65
	v_lshlrev_b32_e32 v24, 16, v66
	v_and_b32_e32 v25, 0xffff0000, v66
	v_lshlrev_b32_e32 v20, 16, v70
	v_and_b32_e32 v21, 0xffff0000, v70
	v_pk_fma_f32 v[6:7], v[6:7], v[170:171], v[22:23] op_sel_hi:[1,0,1]
	v_pk_fma_f32 v[22:23], v[0:1], v[170:171], v[24:25] op_sel_hi:[1,0,1]
	v_mul_f32_e32 v0, v13, v13
	v_mul_f32_e32 v1, v15, v15
	v_pk_fma_f32 v[18:19], v[8:9], v[170:171], v[20:21] op_sel_hi:[1,0,1]
	v_lshlrev_b32_e32 v20, 16, v64
	v_and_b32_e32 v21, 0xffff0000, v64
	v_lshlrev_b32_e32 v26, 16, v67
	v_and_b32_e32 v27, 0xffff0000, v67
	v_fmac_f32_e32 v0, v12, v12
	v_fmac_f32_e32 v1, v14, v14
	v_pk_fma_f32 v[4:5], v[4:5], v[170:171], v[20:21] op_sel_hi:[1,0,1]
	v_pk_fma_f32 v[20:21], v[2:3], v[170:171], v[26:27] op_sel_hi:[1,0,1]
	v_add_f32_e32 v0, v0, v1
	v_mul_f32_e32 v1, v19, v19
	v_mul_f32_e32 v2, v17, v17
	v_fmac_f32_e32 v1, v18, v18
	v_fmac_f32_e32 v2, v16, v16
	v_add_f32_e32 v1, v1, v2
	v_add_f32_e32 v0, v0, v1
	v_mul_f32_e32 v1, v5, v5
	v_mul_f32_e32 v2, v7, v7
	v_fmac_f32_e32 v1, v4, v4
	v_fmac_f32_e32 v2, v6, v6
	v_add_f32_e32 v1, v1, v2
	v_mul_f32_e32 v2, v23, v23
	v_mul_f32_e32 v3, v21, v21
	v_fmac_f32_e32 v2, v22, v22
	v_fmac_f32_e32 v3, v20, v20
	v_add_f32_e32 v2, v2, v3
	v_add_f32_e32 v1, v1, v2
	v_add_f32_e32 v3, v0, v1
	v_cvt_pk_bf16_f32 v8, v12, v13
	v_cvt_pk_bf16_f32 v9, v14, v15
	ds_bpermute_b32 v14, v122, v3
	v_lshl_add_u64 v[0:1], s[14:15], 0, v[72:73]
	v_lshl_add_u64 v[12:13], v[168:169], 1, v[0:1]
	v_cvt_pk_bf16_f32 v10, v18, v19
	v_cvt_pk_bf16_f32 v11, v16, v17
	s_waitcnt lgkmcnt(0)
	v_add_f32_e32 v0, v3, v14
	ds_bpermute_b32 v1, v123, v0
	s_nop 0
	v_readfirstlane_b32 s82, v12
	v_readfirstlane_b32 s83, v13
	ds_write_b128 v234, v[8:11]
	ds_read_b128 v[236:239], v235
	s_nop 1
	s_waitcnt lgkmcnt(0)
	global_store_dwordx4 v244, v[236:239], s[82:83]
	v_cvt_pk_bf16_f32 v2, v4, v5
	v_cvt_pk_bf16_f32 v3, v6, v7
	v_cvt_pk_bf16_f32 v4, v22, v23
	v_cvt_pk_bf16_f32 v5, v20, v21
	s_nop 0
	v_readfirstlane_b32 s84, v12
	v_readfirstlane_b32 s85, v13
	ds_write_b128 v234, v[2:5]
	ds_read_b128 v[240:243], v235
	s_nop 1
	s_waitcnt lgkmcnt(0)
	global_store_dwordx4 v244, v[240:243], s[84:85] offset:256
	s_and_saveexec_b64 s[42:43], s[6:7]
	s_cbranch_execz .LBB0_511
	v_lshl_add_u64 v[2:3], v[88:89], 2, s[16:17]
	s_waitcnt lgkmcnt(0)
	v_add_f32_e32 v0, v0, v1
	global_atomic_add_f32 v[2:3], v0, off

.LBB0_567:
	s_or_b64 exec, exec, s[6:7]
	v_mov_b32_e32 v8, v172
	v_and_b32_e32 v233, 63, v172
	v_lshrrev_b32_e32 v234, 6, v172
	v_mul_u32_u24_e32 v234, 0x7e0, v234
	v_add_u32_e32 v234, 0x20000, v234
	v_and_b32_e32 v235, 15, v233
	v_lshrrev_b32_e32 v230, 4, v233
	v_bfe_u32 v231, v235, 1, 2
	v_xor_b32_e32 v230, v230, v231
	v_lshlrev_b32_e32 v230, 4, v230
	v_lshl_add_u32 v230, v235, 6, v230
	v_add_u32_e32 v230, v230, v234
	v_lshrrev_b32_e32 v235, 2, v233
	v_and_b32_e32 v231, 3, v233
	v_bfe_u32 v232, v235, 1, 2
	v_xor_b32_e32 v231, v231, v232
	v_lshlrev_b32_e32 v231, 4, v231
	v_lshl_add_u32 v231, v235, 6, v231
	v_add_u32_e32 v231, v231, v234
	v_and_b32_e32 v232, 3, v233
	v_lshlrev_b32_e32 v232, 4, v232
	v_mul_u32_u24_e32 v235, 0x5800, v235
	v_add_u32_e32 v232, v232, v235
	s_cmpk_lt_i32 s33, 0xb00
	s_waitcnt lgkmcnt(0)
	s_barrier
	s_cselect_b64 s[6:7], -1, 0
	s_cmpk_gt_i32 s33, 0xaff
	v_readfirstlane_b32 s8, v8
	s_cbranch_scc1 .LBB0_569
	s_ashr_i32 s2, s33, 31
	s_lshr_b32 s2, s2, 29
	s_add_i32 s2, s33, s2
	s_ashr_i32 s9, s2, 3
	s_and_b32 s2, s2, -8
	s_sub_i32 s2, s33, s2
	s_cmp_lt_i32 s2, 0
	s_movk_i32 s10, 0x161
	s_cselect_b32 s10, s10, 0x160
	s_mul_i32 s2, s2, s10
	s_add_i32 s2, s2, s9
	s_mul_hi_i32 s9, s2, 0x2e8ba2e9
	s_lshr_b32 s10, s9, 31
	s_ashr_i32 s9, s9, 4
	s_add_i32 s9, s9, s10
	s_lshl_b32 s10, s9, 2
	s_mulk_i32 s9, 0x58
	s_sub_i32 s2, s2, s9
	s_bfe_i32 s9, s2, 0x80000
	s_bfe_u32 s9, s9, 0x2000d
	s_add_i32 s9, s2, s9
	s_bfe_i32 s11, s9, 0x80000
	s_and_b32 s9, s9, 0xfc
	s_sub_i32 s2, s2, s9
	s_sext_i32_i16 s11, s11
	s_sext_i32_i8 s2, s2
	s_add_i32 s54, s10, s2
	s_ashr_i32 s52, s11, 2

.LBB0_589:
	s_or_b64 exec, exec, s[52:53]
	v_or_b32_e32 v70, s45, v173
	v_mov_b64_e32 v[64:65], s[18:19]
	v_mad_i64_i32 v[66:67], s[52:53], v70, s75, v[64:65]
	v_lshlrev_b64 v[68:69], 1, v[192:193]
	v_lshl_add_u64 v[66:67], v[66:67], 0, v[68:69]
	s_nop 0
	v_readfirstlane_b32 s82, v66
	v_readfirstlane_b32 s83, v67
	ds_write_b128 v230, v[148:151]
	ds_read_b128 v[236:239], v231
	s_nop 1
	s_waitcnt lgkmcnt(0)
	global_store_dwordx4 v232, v[236:239], s[82:83]
	v_or_b32_e32 v66, 1, v70
	v_mad_i64_i32 v[66:67], s[52:53], v66, s75, v[64:65]
	v_lshl_add_u64 v[66:67], v[66:67], 0, v[68:69]
	s_nop 0
	v_readfirstlane_b32 s84, v66
	v_readfirstlane_b32 s85, v67
	ds_write_b128 v230, v[136:139]
	ds_read_b128 v[240:243], v231
	s_nop 1
	s_waitcnt lgkmcnt(0)
	global_store_dwordx4 v232, v[240:243], s[84:85]
	v_or_b32_e32 v66, 2, v70
	v_mad_i64_i32 v[66:67], s[52:53], v66, s75, v[64:65]
	v_lshl_add_u64 v[66:67], v[66:67], 0, v[68:69]
	s_nop 0
	v_readfirstlane_b32 s82, v66
	v_readfirstlane_b32 s83, v67
	ds_write_b128 v230, v[132:135]
	ds_read_b128 v[236:239], v231
	s_nop 1
	s_waitcnt lgkmcnt(0)
	global_store_dwordx4 v232, v[236:239], s[82:83]
	v_or_b32_e32 v66, 3, v70
	v_mad_i64_i32 v[64:65], s[52:53], v66, s75, v[64:65]
	v_lshl_add_u64 v[64:65], v[64:65], 0, v[68:69]
	s_nop 0
	v_readfirstlane_b32 s84, v64
	v_readfirstlane_b32 s85, v65
	ds_write_b128 v230, v[112:115]
	ds_read_b128 v[240:243], v231
	s_nop 1
	s_waitcnt lgkmcnt(0)
	global_store_dwordx4 v232, v[240:243], s[84:85]
	v_fmamk_f32 v64, v140, 0x3a800000, v210
	v_rsq_f32_e32 v90, v64
	v_fmamk_f32 v64, v141, 0x3a800000, v210
	v_rsq_f32_e32 v88, v64
	v_fmamk_f32 v64, v143, 0x3a800000, v210
	v_rsq_f32_e32 v70, v64
	v_pk_mul_f32 v[60:61], v[60:61], v[90:91] op_sel_hi:[1,0]
	v_pk_mul_f32 v[98:99], v[56:57], v[88:89] op_sel_hi:[1,0]
	v_pk_mul_f32 v[96:97], v[58:59], v[88:89] op_sel_hi:[1,0]
	v_pk_mul_f32 v[52:53], v[52:53], v[70:71] op_sel_hi:[1,0]
	v_pk_mul_f32 v[54:55], v[54:55], v[70:71] op_sel_hi:[1,0]
	v_pk_mul_f32 v[62:63], v[62:63], v[90:91] op_sel_hi:[1,0]
	v_mov_b32_dpp v56, v52 row_shr:1 row_mask:0xf bank_mask:0xf bound_ctrl:1
	v_mov_b32_dpp v57, v53 row_shr:1 row_mask:0xf bank_mask:0xf bound_ctrl:1
	v_mov_b32_dpp v58, v54 row_shr:1 row_mask:0xf bank_mask:0xf bound_ctrl:1
	v_mov_b32_dpp v59, v55 row_shr:1 row_mask:0xf bank_mask:0xf bound_ctrl:1
	v_pk_mul_f32 v[56:57], v[120:121], v[56:57]
	v_pk_mul_f32 v[58:59], v[122:123], v[58:59]
	v_pk_fma_f32 v[56:57], v[128:129], v[60:61], v[56:57]
	v_pk_fma_f32 v[58:59], v[130:131], v[62:63], v[58:59]
	v_pk_fma_f32 v[56:57], v[116:117], v[98:99], v[56:57]
	v_pk_fma_f32 v[58:59], v[118:119], v[96:97], v[58:59]
	v_pk_add_f32 v[56:57], v[124:125], v[56:57]
	v_pk_add_f32 v[58:59], v[126:127], v[58:59]
	v_pk_mul_f32 v[66:67], v[56:57], v[56:57]
	v_mov_b64_e32 v[100:101], s[42:43]
	v_pk_mul_f32 v[64:65], v[58:59], v[58:59]
	v_pk_fma_f32 v[66:67], v[66:67], s[40:41], v[100:101] op_sel_hi:[1,0,0] neg_lo:[1,0,0] neg_hi:[1,0,0]
	v_pk_fma_f32 v[64:65], v[64:65], s[40:41], v[100:101] op_sel_hi:[1,0,0] neg_lo:[1,0,0] neg_hi:[1,0,0]
	v_pk_mul_f32 v[66:67], v[56:57], v[66:67]
	v_pk_mul_f32 v[64:65], v[58:59], v[64:65]
	v_exp_f32_e32 v66, v66
	v_exp_f32_e32 v67, v67
	v_exp_f32_e32 v64, v64
	v_exp_f32_e32 v65, v65
	s_addk_i32 s45, 0x80
	v_pk_add_f32 v[66:67], v[66:67], 1.0 op_sel_hi:[1,0]
	s_ashr_i32 s56, s45, 5
	v_rcp_f32_e32 v100, v66
	v_rcp_f32_e32 v101, v67
	v_pk_add_f32 v[64:65], v[64:65], 1.0 op_sel_hi:[1,0]
	s_mul_i32 s47, s56, 3
	v_rcp_f32_e32 v102, v64
	v_rcp_f32_e32 v103, v65
	v_pk_mul_f32 v[64:65], v[48:49], v[90:91] op_sel_hi:[1,0]
	v_pk_mul_f32 v[48:49], v[56:57], v[100:101]
	s_mul_i32 s56, s56, 0x8400
	s_mul_hi_i32 s57, s47, 0x2c00
	v_mov_b32_dpp v92, v60 row_shl:1 row_mask:0xf bank_mask:0xf bound_ctrl:1
	v_mov_b32_dpp v93, v61 row_shl:1 row_mask:0xf bank_mask:0xf bound_ctrl:1
	v_mov_b32_dpp v94, v62 row_shl:1 row_mask:0xf bank_mask:0xf bound_ctrl:1
	v_mov_b32_dpp v95, v63 row_shl:1 row_mask:0xf bank_mask:0xf bound_ctrl:1
	v_pk_mul_f32 v[66:67], v[50:51], v[90:91] op_sel_hi:[1,0]
	v_pk_mul_f32 v[50:51], v[58:59], v[102:103]
	v_pk_mul_f32 v[48:49], v[64:65], v[48:49]
	v_pk_mul_f32 v[50:51], v[66:67], v[50:51]
	v_cvt_pk_bf16_f32 v48, v48, v49
	s_nop 0
	v_cvt_pk_bf16_f32 v49, v50, v51
	s_and_saveexec_b64 s[52:53], s[8:9]
	s_cbranch_execz .LBB0_591
	s_add_u32 s58, s67, s56
	s_addc_u32 s59, s68, s57
	v_lshl_add_u64 v[50:51], v[192:193], 2, s[58:59]
	global_store_dwordx4 v[50:51], v[56:59], off
	s_nop 1
	v_add_co_u32_e32 v56, vcc, 0x2000, v50
	s_nop 1
	v_addc_co_u32_e32 v57, vcc, 0, v51, vcc
	v_add_co_u32_e32 v50, vcc, 0x5000, v50
	global_store_dwordx4 v[56:57], v[64:67], off offset:3072
	s_nop 0
	v_addc_co_u32_e32 v51, vcc, 0, v51, vcc
	global_store_dwordx4 v[50:51], v[60:63], off offset:2048

.LBB0_597:
	s_or_b64 exec, exec, s[52:53]
	v_or_b32_e32 v4, s45, v173
	v_mov_b64_e32 v[0:1], s[18:19]
	v_mad_i64_i32 v[2:3], s[52:53], v4, s75, v[0:1]
	v_lshl_add_u64 v[2:3], v[2:3], 0, v[68:69]
	s_nop 0
	v_readfirstlane_b32 s82, v2
	v_readfirstlane_b32 s83, v3
	ds_write_b128 v230, v[48:51]
	ds_read_b128 v[236:239], v231
	s_nop 1
	s_waitcnt lgkmcnt(0)
	global_store_dwordx4 v232, v[236:239], s[82:83]
	v_or_b32_e32 v2, 1, v4
	v_mad_i64_i32 v[2:3], s[52:53], v2, s75, v[0:1]
	v_lshl_add_u64 v[2:3], v[2:3], 0, v[68:69]
	s_nop 0
	v_readfirstlane_b32 s84, v2
	v_readfirstlane_b32 s85, v3
	ds_write_b128 v230, v[40:43]
	ds_read_b128 v[240:243], v231
	s_nop 1
	s_waitcnt lgkmcnt(0)
	global_store_dwordx4 v232, v[240:243], s[84:85]
	v_or_b32_e32 v2, 2, v4
	v_mad_i64_i32 v[2:3], s[52:53], v2, s75, v[0:1]
	v_lshl_add_u64 v[2:3], v[2:3], 0, v[68:69]
	s_nop 0
	v_readfirstlane_b32 s82, v2
	v_readfirstlane_b32 s83, v3
	ds_write_b128 v230, v[36:39]
	ds_read_b128 v[236:239], v231
	s_nop 1
	s_waitcnt lgkmcnt(0)
	global_store_dwordx4 v232, v[236:239], s[82:83]
	v_or_b32_e32 v2, 3, v4
	v_mad_i64_i32 v[0:1], s[52:53], v2, s75, v[0:1]
	v_lshl_add_u64 v[0:1], v[0:1], 0, v[68:69]
	s_andn2_b64 vcc, exec, s[10:11]
	s_mov_b64 s[10:11], -1
	s_nop 0
	v_readfirstlane_b32 s84, v0
	v_readfirstlane_b32 s85, v1
	ds_write_b128 v230, v[32:35]
	ds_read_b128 v[240:243], v231
	s_nop 1
	s_waitcnt lgkmcnt(0)
	global_store_dwordx4 v232, v[240:243], s[84:85]
	s_cbranch_vccnz .LBB0_574
	s_andn2_b64 vcc, exec, s[16:17]
	s_cbranch_vccnz .LBB0_573
	s_barrier
	s_branch .LBB0_573

.LBB0_718:
	s_or_b64 exec, exec, s[6:7]
	s_waitcnt lgkmcnt(0)
	s_barrier
	s_load_dwordx2 s[6:7], s[0:1], 0xb0
	v_mov_b32_e32 v8, v172
	v_and_b32_e32 v245, 63, v172
	v_lshrrev_b32_e32 v246, 6, v172
	v_mul_u32_u24_e32 v246, 0x7e0, v246
	v_add_u32_e32 v246, 0x20000, v246
	v_and_b32_e32 v247, 15, v245
	v_lshrrev_b32_e32 v234, 4, v245
	v_bfe_u32 v235, v247, 1, 2
	v_xor_b32_e32 v234, v234, v235
	v_lshlrev_b32_e32 v234, 4, v234
	v_lshl_add_u32 v234, v247, 6, v234
	v_add_u32_e32 v234, v234, v246
	v_lshrrev_b32_e32 v247, 2, v245
	v_and_b32_e32 v235, 3, v245
	v_bfe_u32 v244, v247, 1, 2
	v_xor_b32_e32 v235, v235, v244
	v_lshlrev_b32_e32 v235, 4, v235
	v_lshl_add_u32 v235, v247, 6, v235
	v_add_u32_e32 v235, v235, v246
	v_and_b32_e32 v244, 3, v245
	v_lshlrev_b32_e32 v244, 4, v244
	v_mul_u32_u24_e32 v247, 0x800, v247
	v_add_u32_e32 v244, v244, v247
	s_and_b64 vcc, exec, s[4:5]
	v_readfirstlane_b32 s10, v8
	s_cbranch_vccnz .LBB0_724
	s_ashr_i32 s2, s33, 31
	s_lshr_b32 s2, s2, 29
	s_add_i32 s2, s33, s2
	s_and_b32 s8, s2, -8
	s_sub_i32 s11, s33, s8
	s_cmp_gt_i32 s11, -1
	s_cbranch_scc0 .LBB0_721
	s_lshl_b32 s12, s11, 6
	s_cbranch_execz .LBB0_722
	s_branch .LBB0_723

.LBB0_744:
	v_lshl_or_b32 v168, s59, 8, v193
	v_lshl_add_u32 v178, s58, 8, v173
	v_ashrrev_i32_e32 v169, 31, v168
	v_lshlrev_b64 v[176:177], 1, v[168:169]
	v_ashrrev_i32_e32 v179, 31, v178
	v_lshl_add_u64 v[128:129], s[14:15], 0, v[176:177]
	v_lshlrev_b64 v[130:131], 11, v[178:179]
	v_lshl_add_u64 v[132:133], v[128:129], 0, v[130:131]
	global_load_dwordx4 v[198:201], v[132:133], off
	global_load_dwordx4 v[202:205], v[132:133], off offset:256
	v_or_b32_e32 v186, 16, v178
	v_or_b32_e32 v182, 32, v178
	v_or_b32_e32 v174, 48, v178
	v_ashrrev_i32_e32 v187, 31, v186
	v_ashrrev_i32_e32 v183, 31, v182
	v_ashrrev_i32_e32 v175, 31, v174
	v_lshlrev_b64 v[190:191], 11, v[186:187]
	v_lshlrev_b64 v[188:189], 11, v[182:183]
	v_lshlrev_b64 v[184:185], 11, v[174:175]
	v_add_u32_e32 v170, 0x80, v178
	v_lshl_add_u64 v[130:131], s[16:17], 0, v[130:131]
	v_lshl_add_u64 v[132:133], v[128:129], 0, v[190:191]
	v_lshl_add_u64 v[134:135], v[128:129], 0, v[188:189]
	v_lshl_add_u64 v[128:129], v[128:129], 0, v[184:185]
	v_ashrrev_i32_e32 v171, 31, v170
	v_lshl_add_u64 v[206:207], v[130:131], 0, v[176:177]
	global_load_dwordx4 v[148:151], v[132:133], off
	global_load_dwordx4 v[144:147], v[132:133], off offset:256
	global_load_dwordx4 v[140:143], v[134:135], off
	global_load_dwordx4 v[136:139], v[134:135], off offset:256
	s_nop 0
	global_load_dwordx4 v[132:135], v[128:129], off
	s_nop 0
	global_load_dwordx4 v[128:131], v[128:129], off offset:256
	v_lshlrev_b64 v[180:181], 11, v[170:171]
	v_lshl_add_u64 v[210:211], s[14:15], 0, v[180:181]
	v_lshl_add_u64 v[210:211], v[210:211], 0, v[176:177]
	s_waitcnt vmcnt(0)
	v_lshlrev_b32_e32 v212, 16, v198
	v_and_b32_e32 v213, 0xffff0000, v198
	v_lshlrev_b32_e32 v198, 16, v199
	v_and_b32_e32 v199, 0xffff0000, v199
	v_lshlrev_b32_e32 v214, 16, v200
	v_and_b32_e32 v215, 0xffff0000, v200
	v_lshlrev_b32_e32 v200, 16, v201
	v_and_b32_e32 v201, 0xffff0000, v201
	v_lshlrev_b32_e32 v218, 16, v204
	v_and_b32_e32 v219, 0xffff0000, v204
	v_lshlrev_b32_e32 v204, 16, v205
	v_and_b32_e32 v205, 0xffff0000, v205
	v_lshlrev_b32_e32 v216, 16, v202
	v_and_b32_e32 v217, 0xffff0000, v202
	v_lshlrev_b32_e32 v202, 16, v203
	v_and_b32_e32 v203, 0xffff0000, v203
	v_pk_add_f32 v[198:199], v[126:127], v[198:199]
	v_pk_add_f32 v[212:213], v[124:125], v[212:213]
	v_pk_add_f32 v[122:123], v[122:123], v[200:201]
	v_pk_add_f32 v[120:121], v[120:121], v[214:215]
	v_pk_add_f32 v[204:205], v[114:115], v[204:205]
	v_pk_add_f32 v[214:215], v[112:113], v[218:219]
	v_cvt_pk_bf16_f32 v112, v212, v213
	v_cvt_pk_bf16_f32 v113, v198, v199
	v_cvt_pk_bf16_f32 v114, v120, v121
	v_cvt_pk_bf16_f32 v115, v122, v123
	v_pk_add_f32 v[200:201], v[118:119], v[202:203]
	v_pk_add_f32 v[202:203], v[116:117], v[216:217]
	s_nop 0
	v_readfirstlane_b32 s82, v206
	v_readfirstlane_b32 s83, v207
	ds_write_b128 v234, v[112:115]
	ds_read_b128 v[236:239], v235
	s_nop 1
	s_waitcnt lgkmcnt(0)
	global_store_dwordx4 v244, v[236:239], s[82:83]
	v_cvt_pk_bf16_f32 v124, v202, v203
	v_cvt_pk_bf16_f32 v125, v200, v201
	v_cvt_pk_bf16_f32 v126, v214, v215
	v_cvt_pk_bf16_f32 v127, v204, v205
	global_load_dwordx4 v[116:119], v[210:211], off
	global_load_dwordx4 v[112:115], v[210:211], off offset:256
	v_mul_f32_e32 v121, v121, v121
	v_fmac_f32_e32 v121, v120, v120
	v_mul_f32_e32 v120, v123, v123
	v_fmac_f32_e32 v120, v122, v122
	v_add_f32_e32 v120, v121, v120
	v_mul_f32_e32 v121, v203, v203
	v_mul_f32_e32 v122, v201, v201
	v_fmac_f32_e32 v121, v202, v202
	v_fmac_f32_e32 v122, v200, v200
	v_mul_f32_e32 v209, v213, v213
	v_mul_f32_e32 v199, v199, v199
	v_add_f32_e32 v121, v121, v122
	v_mul_f32_e32 v122, v215, v215
	v_mul_f32_e32 v123, v205, v205
	v_fmac_f32_e32 v209, v212, v212
	v_fmac_f32_e32 v199, v198, v198
	v_fmac_f32_e32 v122, v214, v214
	v_fmac_f32_e32 v123, v204, v204
	v_add_f32_e32 v198, v209, v199
	v_add_f32_e32 v122, v122, v123
	v_add_f32_e32 v120, v198, v120
	v_add_f32_e32 v121, v121, v122
	v_and_b32_e32 v122, 64, v197
	v_add_f32_e32 v121, v120, v121
	v_xor_b32_e32 v120, 16, v197
	v_add_u32_e32 v123, 64, v122
	v_cmp_lt_i32_e32 vcc, v120, v123
	s_nop 0
	v_readfirstlane_b32 s84, v206
	v_readfirstlane_b32 s85, v207
	ds_write_b128 v234, v[124:127]
	ds_read_b128 v[240:243], v235
	s_nop 1
	s_waitcnt lgkmcnt(0)
	global_store_dwordx4 v244, v[240:243], s[84:85] offset:256
	s_nop 0
	v_cndmask_b32_e32 v120, v197, v120, vcc
	v_lshlrev_b32_e32 v120, 2, v120
	ds_bpermute_b32 v122, v120, v121
	s_waitcnt lgkmcnt(0)
	v_add_f32_e32 v122, v121, v122
	v_xor_b32_e32 v121, 32, v197
	v_cmp_lt_i32_e32 vcc, v121, v123
	s_nop 1
	v_cndmask_b32_e32 v121, v197, v121, vcc
	v_lshlrev_b32_e32 v121, 2, v121
	ds_bpermute_b32 v123, v121, v122
	s_and_saveexec_b64 s[36:37], s[6:7]
	s_cbranch_execz .LBB0_746
	v_lshl_add_u64 v[124:125], v[178:179], 2, s[18:19]
	s_waitcnt lgkmcnt(0)
	v_add_f32_e32 v122, v122, v123
	global_atomic_add_f32 v[124:125], v122, off
.LBB0_746:
	s_or_b64 exec, exec, s[36:37]
	v_lshlrev_b32_e32 v124, 16, v149
	v_and_b32_e32 v125, 0xffff0000, v149
	v_lshlrev_b32_e32 v126, 16, v150
	v_and_b32_e32 v127, 0xffff0000, v150
	v_lshlrev_b32_e32 v122, 16, v148
	s_waitcnt lgkmcnt(0)
	v_and_b32_e32 v123, 0xffff0000, v148
	v_pk_add_f32 v[110:111], v[110:111], v[124:125]
	v_pk_add_f32 v[124:125], v[104:105], v[126:127]
	v_lshl_add_u64 v[126:127], s[16:17], 0, v[190:191]
	v_lshlrev_b32_e32 v148, 16, v151
	v_and_b32_e32 v149, 0xffff0000, v151
	v_pk_add_f32 v[108:109], v[108:109], v[122:123]
	v_lshl_add_u64 v[126:127], v[126:127], 0, v[176:177]
	v_cvt_pk_bf16_f32 v104, v108, v109
	v_cvt_pk_bf16_f32 v105, v110, v111
	v_pk_add_f32 v[122:123], v[106:107], v[148:149]
	v_cvt_pk_bf16_f32 v106, v124, v125
	v_mul_f32_e32 v109, v109, v109
	v_cvt_pk_bf16_f32 v107, v122, v123
	s_nop 0
	v_readfirstlane_b32 s82, v126
	v_readfirstlane_b32 s83, v127
	ds_write_b128 v234, v[104:107]
	ds_read_b128 v[236:239], v235
	s_nop 1
	s_waitcnt lgkmcnt(0)
	global_store_dwordx4 v244, v[236:239], s[82:83]
	v_fmac_f32_e32 v109, v108, v108
	v_mul_f32_e32 v108, v111, v111
	v_lshlrev_b32_e32 v104, 16, v144
	v_and_b32_e32 v105, 0xffff0000, v144
	v_pk_add_f32 v[150:151], v[100:101], v[104:105]
	v_add_u32_e32 v104, 0x90, v178
	v_lshlrev_b32_e32 v106, 16, v145
	v_and_b32_e32 v107, 0xffff0000, v145
	v_lshlrev_b32_e32 v144, 16, v146
	v_and_b32_e32 v145, 0xffff0000, v146
	v_ashrrev_i32_e32 v105, 31, v104
	v_lshlrev_b32_e32 v146, 16, v147
	v_and_b32_e32 v147, 0xffff0000, v147
	v_pk_add_f32 v[148:149], v[102:103], v[106:107]
	v_pk_add_f32 v[144:145], v[96:97], v[144:145]
	v_cvt_pk_bf16_f32 v96, v150, v151
	v_cvt_pk_bf16_f32 v97, v148, v149
	v_lshlrev_b64 v[106:107], 11, v[104:105]
	v_pk_add_f32 v[146:147], v[98:99], v[146:147]
	v_cvt_pk_bf16_f32 v98, v144, v145
	v_fmac_f32_e32 v108, v110, v110
	v_cvt_pk_bf16_f32 v99, v146, v147
	s_nop 0
	v_readfirstlane_b32 s84, v126
	v_readfirstlane_b32 s85, v127
	ds_write_b128 v234, v[96:99]
	ds_read_b128 v[240:243], v235
	s_nop 1
	s_waitcnt lgkmcnt(0)
	global_store_dwordx4 v244, v[240:243], s[84:85] offset:256
	v_add_f32_e32 v108, v109, v108
	v_mul_f32_e32 v109, v125, v125
	v_lshl_add_u64 v[96:97], s[14:15], 0, v[106:107]
	v_lshl_add_u64 v[96:97], v[96:97], 0, v[176:177]
	global_load_dwordx4 v[100:103], v[96:97], off
	s_nop 0
	global_load_dwordx4 v[96:99], v[96:97], off offset:256
	v_mul_f32_e32 v110, v123, v123
	v_fmac_f32_e32 v109, v124, v124
	v_fmac_f32_e32 v110, v122, v122
	v_add_f32_e32 v109, v109, v110
	v_add_f32_e32 v108, v108, v109
	v_mul_f32_e32 v109, v151, v151
	v_mul_f32_e32 v110, v149, v149
	v_fmac_f32_e32 v109, v150, v150
	v_fmac_f32_e32 v110, v148, v148
	v_add_f32_e32 v109, v109, v110
	v_mul_f32_e32 v110, v145, v145
	v_mul_f32_e32 v111, v147, v147
	v_fmac_f32_e32 v110, v144, v144
	v_fmac_f32_e32 v111, v146, v146
	v_add_f32_e32 v110, v110, v111
	v_add_f32_e32 v109, v109, v110
	v_add_f32_e32 v108, v108, v109
	ds_bpermute_b32 v109, v120, v108
	s_waitcnt lgkmcnt(0)
	v_add_f32_e32 v108, v108, v109
	ds_bpermute_b32 v109, v121, v108
	s_and_saveexec_b64 s[36:37], s[6:7]
	s_cbranch_execz .LBB0_748
	v_lshl_add_u64 v[110:111], v[186:187], 2, s[18:19]
	s_waitcnt lgkmcnt(0)
	v_add_f32_e32 v108, v108, v109
	global_atomic_add_f32 v[110:111], v108, off
.LBB0_748:
	s_or_b64 exec, exec, s[36:37]
	v_lshlrev_b32_e32 v110, 16, v141
	v_and_b32_e32 v111, 0xffff0000, v141
	v_lshlrev_b32_e32 v122, 16, v142
	v_and_b32_e32 v123, 0xffff0000, v142
	v_lshlrev_b32_e32 v108, 16, v140
	s_waitcnt lgkmcnt(0)
	v_and_b32_e32 v109, 0xffff0000, v140
	v_pk_add_f32 v[94:95], v[94:95], v[110:111]
	v_pk_add_f32 v[110:111], v[88:89], v[122:123]
	v_lshl_add_u64 v[122:123], s[16:17], 0, v[188:189]
	v_lshlrev_b32_e32 v124, 16, v143
	v_and_b32_e32 v125, 0xffff0000, v143
	v_pk_add_f32 v[92:93], v[92:93], v[108:109]
	v_lshl_add_u64 v[122:123], v[122:123], 0, v[176:177]
	v_cvt_pk_bf16_f32 v88, v92, v93
	v_cvt_pk_bf16_f32 v89, v94, v95
	v_pk_add_f32 v[108:109], v[90:91], v[124:125]
	v_cvt_pk_bf16_f32 v90, v110, v111
	v_lshlrev_b32_e32 v124, 16, v138
	v_cvt_pk_bf16_f32 v91, v108, v109
	s_nop 0
	v_readfirstlane_b32 s82, v122
	v_readfirstlane_b32 s83, v123
	ds_write_b128 v234, v[88:91]
	ds_read_b128 v[236:239], v235
	s_nop 1
	s_waitcnt lgkmcnt(0)
	global_store_dwordx4 v244, v[236:239], s[82:83]
	v_and_b32_e32 v125, 0xffff0000, v138
	v_lshlrev_b32_e32 v126, 16, v139
	v_lshlrev_b32_e32 v88, 16, v136
	v_and_b32_e32 v89, 0xffff0000, v136
	v_and_b32_e32 v127, 0xffff0000, v139
	v_pk_add_f32 v[138:139], v[84:85], v[88:89]
	v_add_u32_e32 v88, 0xa0, v178
	v_lshlrev_b32_e32 v90, 16, v137
	v_and_b32_e32 v91, 0xffff0000, v137
	v_ashrrev_i32_e32 v89, 31, v88
	v_pk_add_f32 v[136:137], v[86:87], v[90:91]
	v_pk_add_f32 v[124:125], v[80:81], v[124:125]
	v_cvt_pk_bf16_f32 v80, v138, v139
	v_cvt_pk_bf16_f32 v81, v136, v137
	v_lshlrev_b64 v[90:91], 11, v[88:89]
	v_pk_add_f32 v[126:127], v[82:83], v[126:127]
	v_cvt_pk_bf16_f32 v82, v124, v125
	v_mul_f32_e32 v93, v93, v93
	v_cvt_pk_bf16_f32 v83, v126, v127
	s_nop 0
	v_readfirstlane_b32 s84, v122
	v_readfirstlane_b32 s85, v123
	ds_write_b128 v234, v[80:83]
	ds_read_b128 v[240:243], v235
	s_nop 1
	s_waitcnt lgkmcnt(0)
	global_store_dwordx4 v244, v[240:243], s[84:85] offset:256
	v_fmac_f32_e32 v93, v92, v92
	v_mul_f32_e32 v92, v95, v95
	v_lshl_add_u64 v[80:81], s[14:15], 0, v[90:91]
	v_lshl_add_u64 v[80:81], v[80:81], 0, v[176:177]
	global_load_dwordx4 v[84:87], v[80:81], off
	s_nop 0
	global_load_dwordx4 v[80:83], v[80:81], off offset:256
	v_fmac_f32_e32 v92, v94, v94
	v_add_f32_e32 v92, v93, v92
	v_mul_f32_e32 v93, v111, v111
	v_mul_f32_e32 v94, v109, v109
	v_fmac_f32_e32 v93, v110, v110
	v_fmac_f32_e32 v94, v108, v108
	v_add_f32_e32 v93, v93, v94
	v_add_f32_e32 v92, v92, v93
	v_mul_f32_e32 v93, v139, v139
	v_mul_f32_e32 v94, v137, v137
	v_fmac_f32_e32 v93, v138, v138
	v_fmac_f32_e32 v94, v136, v136
	v_add_f32_e32 v93, v93, v94
	v_mul_f32_e32 v94, v125, v125
	v_mul_f32_e32 v95, v127, v127
	v_fmac_f32_e32 v94, v124, v124
	v_fmac_f32_e32 v95, v126, v126
	v_add_f32_e32 v94, v94, v95
	v_add_f32_e32 v93, v93, v94
	v_add_f32_e32 v92, v92, v93
	ds_bpermute_b32 v93, v120, v92
	s_waitcnt lgkmcnt(0)
	v_add_f32_e32 v92, v92, v93
	ds_bpermute_b32 v93, v121, v92
	s_and_saveexec_b64 s[36:37], s[6:7]
	s_cbranch_execz .LBB0_750
	v_lshl_add_u64 v[94:95], v[182:183], 2, s[18:19]
	s_waitcnt lgkmcnt(0)
	v_add_f32_e32 v92, v92, v93
	global_atomic_add_f32 v[94:95], v92, off
.LBB0_750:
	s_or_b64 exec, exec, s[36:37]
	v_lshlrev_b32_e32 v94, 16, v133
	v_and_b32_e32 v95, 0xffff0000, v133
	v_lshlrev_b32_e32 v108, 16, v134
	v_and_b32_e32 v109, 0xffff0000, v134
	v_lshlrev_b32_e32 v92, 16, v132
	s_waitcnt lgkmcnt(0)
	v_and_b32_e32 v93, 0xffff0000, v132
	v_pk_add_f32 v[78:79], v[78:79], v[94:95]
	v_pk_add_f32 v[94:95], v[72:73], v[108:109]
	v_lshl_add_u64 v[108:109], s[16:17], 0, v[184:185]
	v_lshlrev_b32_e32 v110, 16, v135
	v_and_b32_e32 v111, 0xffff0000, v135
	v_pk_add_f32 v[76:77], v[76:77], v[92:93]
	v_lshl_add_u64 v[108:109], v[108:109], 0, v[176:177]
	v_cvt_pk_bf16_f32 v72, v76, v77
	v_cvt_pk_bf16_f32 v73, v78, v79
	v_pk_add_f32 v[92:93], v[74:75], v[110:111]
	v_cvt_pk_bf16_f32 v74, v94, v95
	v_lshlrev_b32_e32 v110, 16, v130
	v_cvt_pk_bf16_f32 v75, v92, v93
	s_nop 0
	v_readfirstlane_b32 s82, v108
	v_readfirstlane_b32 s83, v109
	ds_write_b128 v234, v[72:75]
	ds_read_b128 v[236:239], v235
	s_nop 1
	s_waitcnt lgkmcnt(0)
	global_store_dwordx4 v244, v[236:239], s[82:83]
	v_and_b32_e32 v111, 0xffff0000, v130
	v_lshlrev_b32_e32 v122, 16, v131
	v_lshlrev_b32_e32 v72, 16, v128
	v_and_b32_e32 v73, 0xffff0000, v128
	v_pk_add_f32 v[126:127], v[68:69], v[72:73]
	v_add_u32_e32 v72, 0xb0, v178
	v_lshlrev_b32_e32 v74, 16, v129
	v_and_b32_e32 v75, 0xffff0000, v129
	v_ashrrev_i32_e32 v73, 31, v72
	v_and_b32_e32 v123, 0xffff0000, v131
	v_pk_add_f32 v[124:125], v[70:71], v[74:75]
	v_pk_add_f32 v[110:111], v[64:65], v[110:111]
	v_cvt_pk_bf16_f32 v64, v126, v127
	v_cvt_pk_bf16_f32 v65, v124, v125
	v_lshlrev_b64 v[74:75], 11, v[72:73]
	v_pk_add_f32 v[122:123], v[66:67], v[122:123]
	v_cvt_pk_bf16_f32 v66, v110, v111
	v_mul_f32_e32 v77, v77, v77
	v_cvt_pk_bf16_f32 v67, v122, v123
	s_nop 0
	v_readfirstlane_b32 s84, v108
	v_readfirstlane_b32 s85, v109
	ds_write_b128 v234, v[64:67]
	ds_read_b128 v[240:243], v235
	s_nop 1
	s_waitcnt lgkmcnt(0)
	global_store_dwordx4 v244, v[240:243], s[84:85] offset:256
	v_fmac_f32_e32 v77, v76, v76
	v_mul_f32_e32 v76, v79, v79
	v_lshl_add_u64 v[64:65], s[14:15], 0, v[74:75]
	v_lshl_add_u64 v[64:65], v[64:65], 0, v[176:177]
	global_load_dwordx4 v[68:71], v[64:65], off
	s_nop 0
	global_load_dwordx4 v[64:67], v[64:65], off offset:256
	v_fmac_f32_e32 v76, v78, v78
	v_add_f32_e32 v76, v77, v76
	v_mul_f32_e32 v77, v95, v95
	v_mul_f32_e32 v78, v93, v93
	v_fmac_f32_e32 v77, v94, v94
	v_fmac_f32_e32 v78, v92, v92
	v_add_f32_e32 v77, v77, v78
	v_add_f32_e32 v76, v76, v77
	v_mul_f32_e32 v77, v127, v127
	v_mul_f32_e32 v78, v125, v125
	v_fmac_f32_e32 v77, v126, v126
	v_fmac_f32_e32 v78, v124, v124
	v_add_f32_e32 v77, v77, v78
	v_mul_f32_e32 v78, v111, v111
	v_mul_f32_e32 v79, v123, v123
	v_fmac_f32_e32 v78, v110, v110
	v_fmac_f32_e32 v79, v122, v122
	v_add_f32_e32 v78, v78, v79
	v_add_f32_e32 v77, v77, v78
	v_add_f32_e32 v76, v76, v77
	ds_bpermute_b32 v77, v120, v76
	s_waitcnt lgkmcnt(0)
	v_add_f32_e32 v76, v76, v77
	ds_bpermute_b32 v77, v121, v76
	s_and_saveexec_b64 s[36:37], s[6:7]
	s_cbranch_execz .LBB0_752
	v_lshl_add_u64 v[78:79], v[174:175], 2, s[18:19]
	s_waitcnt lgkmcnt(0)
	v_add_f32_e32 v76, v76, v77
	global_atomic_add_f32 v[78:79], v76, off
.LBB0_752:
	s_or_b64 exec, exec, s[36:37]
	s_waitcnt vmcnt(14)
	v_lshlrev_b32_e32 v76, 16, v116
	s_waitcnt lgkmcnt(0)
	v_and_b32_e32 v77, 0xffff0000, v116
	v_lshlrev_b32_e32 v78, 16, v117
	v_and_b32_e32 v79, 0xffff0000, v117
	v_lshlrev_b32_e32 v94, 16, v119
	v_and_b32_e32 v95, 0xffff0000, v119
	v_pk_add_f32 v[62:63], v[62:63], v[78:79]
	v_pk_add_f32 v[60:61], v[60:61], v[76:77]
	v_pk_add_f32 v[76:77], v[58:59], v[94:95]
	s_waitcnt vmcnt(13)
	v_lshlrev_b32_e32 v94, 16, v113
	v_and_b32_e32 v95, 0xffff0000, v113
	v_lshlrev_b32_e32 v108, 16, v114
	v_and_b32_e32 v109, 0xffff0000, v114
	v_lshlrev_b32_e32 v92, 16, v118
	v_and_b32_e32 v93, 0xffff0000, v118
	v_pk_add_f32 v[54:55], v[54:55], v[94:95]
	v_pk_add_f32 v[94:95], v[48:49], v[108:109]
	v_mul_f32_e32 v48, v61, v61
	v_mul_f32_e32 v49, v63, v63
	v_pk_add_f32 v[78:79], v[56:57], v[92:93]
	v_lshlrev_b32_e32 v92, 16, v112
	v_and_b32_e32 v93, 0xffff0000, v112
	v_lshlrev_b32_e32 v110, 16, v115
	v_and_b32_e32 v111, 0xffff0000, v115
	v_fmac_f32_e32 v48, v60, v60
	v_fmac_f32_e32 v49, v62, v62
	v_pk_add_f32 v[52:53], v[52:53], v[92:93]
	v_pk_add_f32 v[92:93], v[50:51], v[110:111]
	v_add_f32_e32 v48, v48, v49
	v_mul_f32_e32 v49, v79, v79
	v_mul_f32_e32 v50, v77, v77
	v_fmac_f32_e32 v49, v78, v78
	v_fmac_f32_e32 v50, v76, v76
	v_add_f32_e32 v49, v49, v50
	v_add_f32_e32 v48, v48, v49
	v_mul_f32_e32 v49, v53, v53
	v_mul_f32_e32 v50, v55, v55
	v_fmac_f32_e32 v49, v52, v52
	v_fmac_f32_e32 v50, v54, v54
	v_add_f32_e32 v49, v49, v50
	v_mul_f32_e32 v50, v95, v95
	v_mul_f32_e32 v51, v93, v93
	v_fmac_f32_e32 v50, v94, v94
	v_fmac_f32_e32 v51, v92, v92
	v_add_f32_e32 v50, v50, v51
	v_add_f32_e32 v49, v49, v50
	v_add_f32_e32 v51, v48, v49
	v_cvt_pk_bf16_f32 v56, v60, v61
	v_cvt_pk_bf16_f32 v57, v62, v63
	ds_bpermute_b32 v62, v120, v51
	v_lshl_add_u64 v[48:49], s[16:17], 0, v[180:181]
	v_lshl_add_u64 v[60:61], v[168:169], 1, v[48:49]
	v_cvt_pk_bf16_f32 v58, v78, v79
	v_cvt_pk_bf16_f32 v59, v76, v77
	s_waitcnt lgkmcnt(0)
	v_add_f32_e32 v48, v51, v62
	ds_bpermute_b32 v49, v121, v48
	s_nop 0
	v_readfirstlane_b32 s82, v60
	v_readfirstlane_b32 s83, v61
	ds_write_b128 v234, v[56:59]
	ds_read_b128 v[236:239], v235
	s_nop 1
	s_waitcnt lgkmcnt(0)
	global_store_dwordx4 v244, v[236:239], s[82:83]
	v_cvt_pk_bf16_f32 v50, v52, v53
	v_cvt_pk_bf16_f32 v51, v54, v55
	v_cvt_pk_bf16_f32 v52, v94, v95
	v_cvt_pk_bf16_f32 v53, v92, v93
	s_nop 0
	v_readfirstlane_b32 s84, v60
	v_readfirstlane_b32 s85, v61
	ds_write_b128 v234, v[50:53]
	ds_read_b128 v[240:243], v235
	s_nop 1
	s_waitcnt lgkmcnt(0)
	global_store_dwordx4 v244, v[240:243], s[84:85] offset:256
	s_and_saveexec_b64 s[36:37], s[6:7]
	s_cbranch_execz .LBB0_754
	v_lshl_add_u64 v[50:51], v[170:171], 2, s[18:19]
	s_waitcnt lgkmcnt(0)
	v_add_f32_e32 v48, v48, v49
	global_atomic_add_f32 v[50:51], v48, off
.LBB0_754:
	s_or_b64 exec, exec, s[36:37]
	s_waitcnt vmcnt(11)
	v_lshlrev_b32_e32 v48, 16, v100
	s_waitcnt lgkmcnt(0)
	v_and_b32_e32 v49, 0xffff0000, v100
	v_lshlrev_b32_e32 v50, 16, v101
	v_and_b32_e32 v51, 0xffff0000, v101
	v_lshlrev_b32_e32 v54, 16, v103
	v_and_b32_e32 v55, 0xffff0000, v103
	v_pk_add_f32 v[46:47], v[46:47], v[50:51]
	v_pk_add_f32 v[44:45], v[44:45], v[48:49]
	v_pk_add_f32 v[48:49], v[42:43], v[54:55]
	s_waitcnt vmcnt(10)
	v_lshlrev_b32_e32 v54, 16, v97
	v_and_b32_e32 v55, 0xffff0000, v97
	v_lshlrev_b32_e32 v56, 16, v98
	v_and_b32_e32 v57, 0xffff0000, v98
	v_lshlrev_b32_e32 v52, 16, v102
	v_and_b32_e32 v53, 0xffff0000, v102
	v_pk_add_f32 v[38:39], v[38:39], v[54:55]
	v_pk_add_f32 v[54:55], v[32:33], v[56:57]
	v_mul_f32_e32 v32, v45, v45
	v_mul_f32_e32 v33, v47, v47
	v_pk_add_f32 v[50:51], v[40:41], v[52:53]
	v_lshlrev_b32_e32 v52, 16, v96
	v_and_b32_e32 v53, 0xffff0000, v96
	v_lshlrev_b32_e32 v58, 16, v99
	v_and_b32_e32 v59, 0xffff0000, v99
	v_fmac_f32_e32 v32, v44, v44
	v_fmac_f32_e32 v33, v46, v46
	v_pk_add_f32 v[36:37], v[36:37], v[52:53]
	v_pk_add_f32 v[52:53], v[34:35], v[58:59]
	v_add_f32_e32 v32, v32, v33
	v_mul_f32_e32 v33, v51, v51
	v_mul_f32_e32 v34, v49, v49
	v_fmac_f32_e32 v33, v50, v50
	v_fmac_f32_e32 v34, v48, v48
	v_add_f32_e32 v33, v33, v34
	v_add_f32_e32 v32, v32, v33
	v_mul_f32_e32 v33, v37, v37
	v_mul_f32_e32 v34, v39, v39
	v_fmac_f32_e32 v33, v36, v36
	v_fmac_f32_e32 v34, v38, v38
	v_add_f32_e32 v33, v33, v34
	v_mul_f32_e32 v34, v55, v55
	v_mul_f32_e32 v35, v53, v53
	v_fmac_f32_e32 v34, v54, v54
	v_fmac_f32_e32 v35, v52, v52
	v_add_f32_e32 v34, v34, v35
	v_add_f32_e32 v33, v33, v34
	v_add_f32_e32 v35, v32, v33
	v_cvt_pk_bf16_f32 v40, v44, v45
	v_cvt_pk_bf16_f32 v41, v46, v47
	ds_bpermute_b32 v46, v120, v35
	v_lshl_add_u64 v[32:33], s[16:17], 0, v[106:107]
	v_lshl_add_u64 v[44:45], v[168:169], 1, v[32:33]
	v_cvt_pk_bf16_f32 v42, v50, v51
	v_cvt_pk_bf16_f32 v43, v48, v49
	s_waitcnt lgkmcnt(0)
	v_add_f32_e32 v32, v35, v46
	ds_bpermute_b32 v33, v121, v32
	s_nop 0
	v_readfirstlane_b32 s82, v44
	v_readfirstlane_b32 s83, v45
	ds_write_b128 v234, v[40:43]
	ds_read_b128 v[236:239], v235
	s_nop 1
	s_waitcnt lgkmcnt(0)
	global_store_dwordx4 v244, v[236:239], s[82:83]
	v_cvt_pk_bf16_f32 v34, v36, v37
	v_cvt_pk_bf16_f32 v35, v38, v39
	v_cvt_pk_bf16_f32 v36, v54, v55
	v_cvt_pk_bf16_f32 v37, v52, v53
	s_nop 0
	v_readfirstlane_b32 s84, v44
	v_readfirstlane_b32 s85, v45
	ds_write_b128 v234, v[34:37]
	ds_read_b128 v[240:243], v235
	s_nop 1
	s_waitcnt lgkmcnt(0)
	global_store_dwordx4 v244, v[240:243], s[84:85] offset:256
	s_and_saveexec_b64 s[36:37], s[6:7]
	s_cbranch_execz .LBB0_756
	v_lshl_add_u64 v[34:35], v[104:105], 2, s[18:19]
	s_waitcnt lgkmcnt(0)
	v_add_f32_e32 v32, v32, v33
	global_atomic_add_f32 v[34:35], v32, off
.LBB0_756:
	s_or_b64 exec, exec, s[36:37]
	s_waitcnt vmcnt(9)
	v_lshlrev_b32_e32 v32, 16, v84
	s_waitcnt lgkmcnt(0)
	v_and_b32_e32 v33, 0xffff0000, v84
	v_lshlrev_b32_e32 v34, 16, v85
	v_and_b32_e32 v35, 0xffff0000, v85
	v_lshlrev_b32_e32 v38, 16, v87
	v_and_b32_e32 v39, 0xffff0000, v87
	v_pk_add_f32 v[30:31], v[30:31], v[34:35]
	v_pk_add_f32 v[28:29], v[28:29], v[32:33]
	v_pk_add_f32 v[32:33], v[26:27], v[38:39]
	s_waitcnt vmcnt(8)
	v_lshlrev_b32_e32 v38, 16, v81
	v_and_b32_e32 v39, 0xffff0000, v81
	v_lshlrev_b32_e32 v40, 16, v82
	v_and_b32_e32 v41, 0xffff0000, v82
	v_lshlrev_b32_e32 v36, 16, v86
	v_and_b32_e32 v37, 0xffff0000, v86
	v_pk_add_f32 v[22:23], v[22:23], v[38:39]
	v_pk_add_f32 v[38:39], v[16:17], v[40:41]
	v_mul_f32_e32 v16, v29, v29
	v_mul_f32_e32 v17, v31, v31
	v_pk_add_f32 v[34:35], v[24:25], v[36:37]
	v_lshlrev_b32_e32 v36, 16, v80
	v_and_b32_e32 v37, 0xffff0000, v80
	v_lshlrev_b32_e32 v42, 16, v83
	v_and_b32_e32 v43, 0xffff0000, v83
	v_fmac_f32_e32 v16, v28, v28
	v_fmac_f32_e32 v17, v30, v30
	v_pk_add_f32 v[20:21], v[20:21], v[36:37]
	v_pk_add_f32 v[36:37], v[18:19], v[42:43]
	v_add_f32_e32 v16, v16, v17
	v_mul_f32_e32 v17, v35, v35
	v_mul_f32_e32 v18, v33, v33
	v_fmac_f32_e32 v17, v34, v34
	v_fmac_f32_e32 v18, v32, v32
	v_add_f32_e32 v17, v17, v18
	v_add_f32_e32 v16, v16, v17
	v_mul_f32_e32 v17, v21, v21
	v_mul_f32_e32 v18, v23, v23
	v_fmac_f32_e32 v17, v20, v20
	v_fmac_f32_e32 v18, v22, v22
	v_add_f32_e32 v17, v17, v18
	v_mul_f32_e32 v18, v39, v39
	v_mul_f32_e32 v19, v37, v37
	v_fmac_f32_e32 v18, v38, v38
	v_fmac_f32_e32 v19, v36, v36
	v_add_f32_e32 v18, v18, v19
	v_add_f32_e32 v17, v17, v18
	v_add_f32_e32 v19, v16, v17
	v_cvt_pk_bf16_f32 v24, v28, v29
	v_cvt_pk_bf16_f32 v25, v30, v31
	ds_bpermute_b32 v30, v120, v19
	v_lshl_add_u64 v[16:17], s[16:17], 0, v[90:91]
	v_lshl_add_u64 v[28:29], v[168:169], 1, v[16:17]
	v_cvt_pk_bf16_f32 v26, v34, v35
	v_cvt_pk_bf16_f32 v27, v32, v33
	s_waitcnt lgkmcnt(0)
	v_add_f32_e32 v16, v19, v30
	ds_bpermute_b32 v17, v121, v16
	s_nop 0
	v_readfirstlane_b32 s82, v28
	v_readfirstlane_b32 s83, v29
	ds_write_b128 v234, v[24:27]
	ds_read_b128 v[236:239], v235
	s_nop 1
	s_waitcnt lgkmcnt(0)
	global_store_dwordx4 v244, v[236:239], s[82:83]
	v_cvt_pk_bf16_f32 v18, v20, v21
	v_cvt_pk_bf16_f32 v19, v22, v23
	v_cvt_pk_bf16_f32 v20, v38, v39
	v_cvt_pk_bf16_f32 v21, v36, v37
	s_nop 0
	v_readfirstlane_b32 s84, v28
	v_readfirstlane_b32 s85, v29
	ds_write_b128 v234, v[18:21]
	ds_read_b128 v[240:243], v235
	s_nop 1
	s_waitcnt lgkmcnt(0)
	global_store_dwordx4 v244, v[240:243], s[84:85] offset:256
	s_and_saveexec_b64 s[36:37], s[6:7]
	s_cbranch_execz .LBB0_758
	v_lshl_add_u64 v[18:19], v[88:89], 2, s[18:19]
	s_waitcnt lgkmcnt(0)
	v_add_f32_e32 v16, v16, v17
	global_atomic_add_f32 v[18:19], v16, off
.LBB0_758:
	s_or_b64 exec, exec, s[36:37]
	s_waitcnt vmcnt(7)
	v_lshlrev_b32_e32 v16, 16, v68
	s_waitcnt lgkmcnt(0)
	v_and_b32_e32 v17, 0xffff0000, v68
	v_lshlrev_b32_e32 v18, 16, v69
	v_and_b32_e32 v19, 0xffff0000, v69
	v_lshlrev_b32_e32 v22, 16, v71
	v_and_b32_e32 v23, 0xffff0000, v71
	v_pk_add_f32 v[14:15], v[14:15], v[18:19]
	v_pk_add_f32 v[12:13], v[12:13], v[16:17]
	v_pk_add_f32 v[16:17], v[10:11], v[22:23]
	s_waitcnt vmcnt(6)
	v_lshlrev_b32_e32 v22, 16, v65
	v_and_b32_e32 v23, 0xffff0000, v65
	v_lshlrev_b32_e32 v24, 16, v66
	v_and_b32_e32 v25, 0xffff0000, v66
	v_lshlrev_b32_e32 v20, 16, v70
	v_and_b32_e32 v21, 0xffff0000, v70
	v_pk_add_f32 v[6:7], v[6:7], v[22:23]
	v_pk_add_f32 v[22:23], v[0:1], v[24:25]
	v_mul_f32_e32 v0, v13, v13
	v_mul_f32_e32 v1, v15, v15
	v_pk_add_f32 v[18:19], v[8:9], v[20:21]
	v_lshlrev_b32_e32 v20, 16, v64
	v_and_b32_e32 v21, 0xffff0000, v64
	v_lshlrev_b32_e32 v26, 16, v67
	v_and_b32_e32 v27, 0xffff0000, v67
	v_fmac_f32_e32 v0, v12, v12
	v_fmac_f32_e32 v1, v14, v14
	v_pk_add_f32 v[4:5], v[4:5], v[20:21]
	v_pk_add_f32 v[20:21], v[2:3], v[26:27]
	v_add_f32_e32 v0, v0, v1
	v_mul_f32_e32 v1, v19, v19
	v_mul_f32_e32 v2, v17, v17
	v_fmac_f32_e32 v1, v18, v18
	v_fmac_f32_e32 v2, v16, v16
	v_add_f32_e32 v1, v1, v2
	v_add_f32_e32 v0, v0, v1
	v_mul_f32_e32 v1, v5, v5
	v_mul_f32_e32 v2, v7, v7
	v_fmac_f32_e32 v1, v4, v4
	v_fmac_f32_e32 v2, v6, v6
	v_add_f32_e32 v1, v1, v2
	v_mul_f32_e32 v2, v23, v23
	v_mul_f32_e32 v3, v21, v21
	v_fmac_f32_e32 v2, v22, v22
	v_fmac_f32_e32 v3, v20, v20
	v_add_f32_e32 v2, v2, v3
	v_add_f32_e32 v1, v1, v2
	v_add_f32_e32 v3, v0, v1
	v_cvt_pk_bf16_f32 v8, v12, v13
	v_cvt_pk_bf16_f32 v9, v14, v15
	ds_bpermute_b32 v14, v120, v3
	v_lshl_add_u64 v[0:1], s[16:17], 0, v[74:75]
	v_lshl_add_u64 v[12:13], v[168:169], 1, v[0:1]
	v_cvt_pk_bf16_f32 v10, v18, v19
	v_cvt_pk_bf16_f32 v11, v16, v17
	s_waitcnt lgkmcnt(0)
	v_add_f32_e32 v0, v3, v14
	ds_bpermute_b32 v1, v121, v0
	s_nop 0
	v_readfirstlane_b32 s82, v12
	v_readfirstlane_b32 s83, v13
	ds_write_b128 v234, v[8:11]
	ds_read_b128 v[236:239], v235
	s_nop 1
	s_waitcnt lgkmcnt(0)
	global_store_dwordx4 v244, v[236:239], s[82:83]
	v_cvt_pk_bf16_f32 v2, v4, v5
	v_cvt_pk_bf16_f32 v3, v6, v7
	v_cvt_pk_bf16_f32 v4, v22, v23
	v_cvt_pk_bf16_f32 v5, v20, v21
	s_nop 0
	v_readfirstlane_b32 s84, v12
	v_readfirstlane_b32 s85, v13
	ds_write_b128 v234, v[2:5]
	ds_read_b128 v[240:243], v235
	s_nop 1
	s_waitcnt lgkmcnt(0)
	global_store_dwordx4 v244, v[240:243], s[84:85] offset:256
	s_and_saveexec_b64 s[36:37], s[6:7]
	s_cbranch_execz .LBB0_760
	v_lshl_add_u64 v[2:3], v[72:73], 2, s[18:19]
	s_waitcnt lgkmcnt(0)
	v_add_f32_e32 v0, v0, v1
	global_atomic_add_f32 v[2:3], v0, off
